# same as previous without the LoRA operand load batching in rwprep stage 2
# speedup vs baseline: 1.0459x; 1.0459x over previous
.LBB0_249:
	s_or_b64 exec, exec, s[0:1]
	v_ashrrev_i32_e32 v37, 4, v60
	v_add_u32_e32 v75, v37, v0
	s_add_i32 s4, s26, -3
	v_mul_lo_u32 v37, v75, s74
	v_sub_u32_e32 v40, v54, v37
	v_add_u32_e32 v39, s4, v75
	v_ashrrev_i32_e32 v41, 31, v40
	v_cmp_lt_i32_e32 vcc, -1, v39
	v_mov_b32_e32 v38, 0
	v_mov_b32_e32 v47, 0
	s_and_saveexec_b64 s[0:1], vcc
	s_cbranch_execz .LBB0_251
	v_mov_b64_e32 v[42:43], s[30:31]
	v_mad_u64_u32 v[42:43], s[16:17], v39, s69, v[42:43]
	s_lshl_b32 s72, s36, 1
	v_lshl_add_u64 v[42:43], v[42:43], 0, s[72:73]
	v_lshl_add_u64 v[42:43], v[40:41], 1, v[42:43]
	global_load_ushort v47, v[42:43], off offset:768
.LBB0_251:
	s_or_b64 exec, exec, s[0:1]
	v_cmp_lt_i32_e32 vcc, -2, v39
	s_and_saveexec_b64 s[0:1], vcc
	s_cbranch_execz .LBB0_253
	v_add_u32_e32 v37, 1, v39
	v_mov_b64_e32 v[42:43], s[30:31]
	v_mad_u64_u32 v[42:43], s[16:17], v37, s69, v[42:43]
	s_lshl_b32 s72, s36, 1
	v_lshl_add_u64 v[42:43], v[42:43], 0, s[72:73]
	v_lshl_add_u64 v[42:43], v[40:41], 1, v[42:43]
	global_load_ushort v38, v[42:43], off offset:768
.LBB0_253:
	s_or_b64 exec, exec, s[0:1]
	v_cmp_lt_i32_e32 vcc, -3, v39
	v_mov_b32_e32 v37, 0
	v_mov_b32_e32 v51, 0
	s_and_saveexec_b64 s[0:1], vcc
	s_cbranch_execz .LBB0_255
	v_add_u32_e32 v39, 2, v39
	v_mov_b64_e32 v[42:43], s[30:31]
	v_mad_u64_u32 v[42:43], s[16:17], v39, s69, v[42:43]
	s_lshl_b32 s72, s36, 1
	v_lshl_add_u64 v[42:43], v[42:43], 0, s[72:73]
	v_lshl_add_u64 v[42:43], v[40:41], 1, v[42:43]
	global_load_ushort v51, v[42:43], off offset:768

.LBB0_257:
	s_or_b64 exec, exec, s[0:1]
	v_ashrrev_i32_e32 v39, 4, v59
	v_add_u32_e32 v81, v39, v35
	v_mul_lo_u32 v39, v81, s74
	v_sub_u32_e32 v42, v34, v39
	v_add_u32_e32 v39, s4, v81
	v_ashrrev_i32_e32 v43, 31, v42
	v_cmp_lt_i32_e32 vcc, -1, v39
	v_mov_b32_e32 v48, 0
	v_mov_b32_e32 v50, 0
	s_and_saveexec_b64 s[0:1], vcc
	s_cbranch_execz .LBB0_259
	v_mov_b64_e32 v[44:45], s[30:31]
	v_mad_u64_u32 v[44:45], s[16:17], v39, s69, v[44:45]
	s_lshl_b32 s72, s36, 1
	v_lshl_add_u64 v[44:45], v[44:45], 0, s[72:73]
	v_lshl_add_u64 v[44:45], v[42:43], 1, v[44:45]
	global_load_ushort v50, v[44:45], off offset:768
.LBB0_259:
	s_or_b64 exec, exec, s[0:1]
	v_cmp_lt_i32_e32 vcc, -2, v39
	s_and_saveexec_b64 s[0:1], vcc
	s_cbranch_execz .LBB0_261
	v_add_u32_e32 v46, 1, v39
	v_mov_b64_e32 v[44:45], s[30:31]
	v_mad_u64_u32 v[44:45], s[16:17], v46, s69, v[44:45]
	s_lshl_b32 s72, s36, 1
	v_lshl_add_u64 v[44:45], v[44:45], 0, s[72:73]
	v_lshl_add_u64 v[44:45], v[42:43], 1, v[44:45]
	global_load_ushort v48, v[44:45], off offset:768
.LBB0_261:
	s_or_b64 exec, exec, s[0:1]
	v_cmp_lt_i32_e32 vcc, -3, v39
	v_mov_b32_e32 v46, 0
	v_mov_b32_e32 v53, 0
	s_and_saveexec_b64 s[0:1], vcc
	s_cbranch_execz .LBB0_263
	v_add_u32_e32 v39, 2, v39
	v_mov_b64_e32 v[44:45], s[30:31]
	v_mad_u64_u32 v[44:45], s[16:17], v39, s69, v[44:45]
	s_lshl_b32 s72, s36, 1
	v_lshl_add_u64 v[44:45], v[44:45], 0, s[72:73]
	v_lshl_add_u64 v[44:45], v[42:43], 1, v[44:45]
	global_load_ushort v53, v[44:45], off offset:768
.LBB0_263:
	s_or_b64 exec, exec, s[0:1]
	v_add_u32_e32 v39, s26, v81
	v_cmp_lt_i32_e32 vcc, -1, v39
	s_and_saveexec_b64 s[0:1], vcc
	s_cbranch_execz .LBB0_265
	v_mov_b64_e32 v[44:45], s[30:31]
	v_mad_u64_u32 v[44:45], s[16:17], v39, s69, v[44:45]
	s_lshl_b32 s72, s36, 1
	v_lshl_add_u64 v[44:45], v[44:45], 0, s[72:73]
	v_lshl_add_u64 v[44:45], v[42:43], 1, v[44:45]
	global_load_ushort v46, v[44:45], off offset:768
.LBB0_265:
	s_or_b64 exec, exec, s[0:1]
	v_add_u32_e32 v39, 0x400, v54
	v_mul_hi_i32 v44, v39, s87
	v_lshrrev_b32_e32 v45, 31, v44
	v_ashrrev_i32_e32 v44, 4, v44
	v_add_u32_e32 v82, v44, v45
	v_mul_lo_u32 v44, v82, s74
	v_sub_u32_e32 v44, v39, v44
	v_add_u32_e32 v61, s4, v82
	v_ashrrev_i32_e32 v45, 31, v44
	v_cmp_lt_i32_e32 vcc, -1, v61
	v_mov_b32_e32 v49, 0
	v_mov_b32_e32 v52, 0
	s_and_saveexec_b64 s[0:1], vcc
	s_cbranch_execz .LBB0_267
	v_mov_b64_e32 v[62:63], s[30:31]
	v_mad_u64_u32 v[62:63], s[4:5], v61, s69, v[62:63]
	s_lshl_b32 s72, s36, 1
	v_lshl_add_u64 v[62:63], v[62:63], 0, s[72:73]
	v_lshl_add_u64 v[62:63], v[44:45], 1, v[62:63]
	global_load_ushort v52, v[62:63], off offset:768
.LBB0_267:
	s_or_b64 exec, exec, s[0:1]
	v_cmp_lt_i32_e32 vcc, -2, v61
	s_and_saveexec_b64 s[0:1], vcc
	s_cbranch_execz .LBB0_269
	v_add_u32_e32 v39, 1, v61
	v_mov_b64_e32 v[62:63], s[30:31]
	v_mad_u64_u32 v[62:63], s[4:5], v39, s69, v[62:63]
	s_lshl_b32 s72, s36, 1
	v_lshl_add_u64 v[62:63], v[62:63], 0, s[72:73]
	v_lshl_add_u64 v[62:63], v[44:45], 1, v[62:63]
	global_load_ushort v49, v[62:63], off offset:768
.LBB0_269:
	s_or_b64 exec, exec, s[0:1]
	v_cmp_lt_i32_e32 vcc, -3, v61
	v_mov_b32_e32 v39, 0
	v_mov_b32_e32 v58, 0
	s_and_saveexec_b64 s[0:1], vcc
	s_cbranch_execz .LBB0_271
	v_add_u32_e32 v58, 2, v61
	v_mov_b64_e32 v[62:63], s[30:31]
	v_mad_u64_u32 v[62:63], s[4:5], v58, s69, v[62:63]
	s_lshl_b32 s72, s36, 1
	v_lshl_add_u64 v[62:63], v[62:63], 0, s[72:73]
	v_lshl_add_u64 v[62:63], v[44:45], 1, v[62:63]
	global_load_ushort v58, v[62:63], off offset:768
.LBB0_271:
	s_or_b64 exec, exec, s[0:1]
	v_add_u32_e32 v61, s26, v82
	v_cmp_lt_i32_e32 vcc, -1, v61
	s_and_saveexec_b64 s[0:1], vcc
	s_cbranch_execz .LBB0_273
	v_mov_b64_e32 v[62:63], s[30:31]
	v_mad_u64_u32 v[62:63], s[4:5], v61, s69, v[62:63]
	s_lshl_b32 s72, s36, 1
	v_lshl_add_u64 v[62:63], v[62:63], 0, s[72:73]
	v_lshl_add_u64 v[62:63], v[44:45], 1, v[62:63]
	global_load_ushort v39, v[62:63], off offset:768
.LBB0_273:
	s_or_b64 exec, exec, s[0:1]
	s_waitcnt vmcnt(0)
	v_lshlrev_b32_e32 v47, 16, v47
	v_lshlrev_b32_e32 v38, 16, v38
	v_lshlrev_b32_e32 v51, 16, v51
	v_lshlrev_b32_e32 v37, 16, v37
	v_lshlrev_b32_e32 v50, 16, v50
	v_lshlrev_b32_e32 v48, 16, v48
	v_lshlrev_b32_e32 v53, 16, v53
	v_lshlrev_b32_e32 v46, 16, v46
	v_lshlrev_b32_e32 v52, 16, v52
	v_lshlrev_b32_e32 v49, 16, v49
	v_lshlrev_b32_e32 v58, 16, v58
	v_lshlrev_b32_e32 v39, 16, v39
	s_waitcnt lgkmcnt(0)
	s_barrier
	s_and_saveexec_b64 s[16:17], s[10:11]
	s_cbranch_execz .LBB0_275
	v_lshrrev_b32_e32 v60, 3, v60
	v_add_u32_e32 v60, v60, v0
	v_mul_lo_u32 v60, v60, 48
	v_sub_u32_e32 v60, v54, v60
	v_lshl_add_u32 v60, v60, 2, 0
	v_add_u32_e32 v94, 0x13700, v60
	v_add_u32_e32 v96, 0x13a00, v60
	v_add_u32_e32 v98, 0x12200, v60
	ds_read_b32 v94, v94
	ds_read_b32 v96, v96
	ds_read_b32 v98, v98
	s_waitcnt vmcnt(0)
	v_lshlrev_b32_e32 v97, 16, v18
	v_add_u32_e32 v61, 0x12ec0, v60
	v_add_u32_e32 v63, 0x12e00, v60
	v_add_u32_e32 v84, 0x131c0, v60
	s_waitcnt lgkmcnt(0)
	v_fmac_f32_e32 v96, v98, v97
	v_add_u32_e32 v98, 0x122c0, v60
	ds_read_b32 v98, v98
	v_and_b32_e32 v97, 0xffff0000, v18
	v_add_u32_e32 v86, 0x13100, v60
	v_add_u32_e32 v88, 0x134c0, v60
	v_add_u32_e32 v90, 0x13400, v60
	s_waitcnt lgkmcnt(0)
	v_fmac_f32_e32 v96, v98, v97
	v_add_u32_e32 v98, 0x12380, v60
	ds_read_b32 v98, v98
	v_lshlrev_b32_e32 v97, 16, v19
	v_add_u32_e32 v92, 0x137c0, v60
	ds_read_b32 v61, v61
	ds_read_b32 v63, v63
	ds_read_b32 v84, v84
	ds_read_b32 v86, v86
	ds_read_b32 v88, v88
	ds_read_b32 v90, v90
	ds_read_b32 v92, v92
	s_waitcnt lgkmcnt(7)
	v_fmac_f32_e32 v96, v98, v97
	v_add_u32_e32 v98, 0x12440, v60
	ds_read_b32 v98, v98
	v_and_b32_e32 v97, 0xffff0000, v19
	v_lshlrev_b32_e32 v62, 16, v64
	v_lshlrev_b32_e32 v83, 16, v57
	v_lshlrev_b32_e32 v85, 16, v66
	s_waitcnt lgkmcnt(0)
	v_fmac_f32_e32 v96, v98, v97
	v_add_u32_e32 v98, 0x12500, v60
	ds_read_b32 v98, v98
	v_lshlrev_b32_e32 v97, 16, v20
	v_lshlrev_b32_e32 v89, 16, v68
	v_lshlrev_b32_e32 v93, 16, v70
	v_lshlrev_b32_e32 v87, 16, v65
	s_waitcnt lgkmcnt(0)
	v_fmac_f32_e32 v96, v98, v97
	v_add_u32_e32 v98, 0x125c0, v60
	ds_read_b32 v98, v98
	v_and_b32_e32 v97, 0xffff0000, v20
	v_lshlrev_b32_e32 v91, 16, v67
	v_lshlrev_b32_e32 v95, 16, v69
	s_waitcnt lgkmcnt(0)
	v_fmac_f32_e32 v96, v98, v97
	v_add_u32_e32 v98, 0x12680, v60
	ds_read_b32 v98, v98
	v_lshlrev_b32_e32 v97, 16, v21
	s_waitcnt lgkmcnt(0)
	v_fmac_f32_e32 v96, v98, v97
	v_add_u32_e32 v98, 0x12740, v60
	ds_read_b32 v98, v98
	v_and_b32_e32 v97, 0xffff0000, v21
	s_waitcnt lgkmcnt(0)
	v_fmac_f32_e32 v96, v98, v97
	v_add_u32_e32 v98, 0x12800, v60
	ds_read_b32 v98, v98
	v_lshlrev_b32_e32 v97, 16, v14
	s_waitcnt lgkmcnt(0)
	v_fmac_f32_e32 v96, v98, v97
	v_add_u32_e32 v98, 0x128c0, v60
	ds_read_b32 v98, v98
	v_and_b32_e32 v97, 0xffff0000, v14
	s_waitcnt lgkmcnt(0)
	v_fmac_f32_e32 v96, v98, v97
	v_add_u32_e32 v98, 0x12980, v60
	ds_read_b32 v98, v98
	v_lshlrev_b32_e32 v97, 16, v15
	s_waitcnt lgkmcnt(0)
	v_fmac_f32_e32 v96, v98, v97
	v_add_u32_e32 v98, 0x12a40, v60
	ds_read_b32 v98, v98
	v_and_b32_e32 v97, 0xffff0000, v15
	s_waitcnt lgkmcnt(0)
	v_fmac_f32_e32 v96, v98, v97
	v_add_u32_e32 v98, 0x12b00, v60
	ds_read_b32 v98, v98
	v_lshlrev_b32_e32 v97, 16, v16
	s_waitcnt lgkmcnt(0)
	v_fmac_f32_e32 v96, v98, v97
	v_add_u32_e32 v98, 0x12bc0, v60
	ds_read_b32 v98, v98
	v_and_b32_e32 v97, 0xffff0000, v16
	s_waitcnt lgkmcnt(0)
	v_fmac_f32_e32 v96, v98, v97
	v_add_u32_e32 v98, 0x12c80, v60
	ds_read_b32 v98, v98
	v_add_u32_e32 v60, 0x12d40, v60
	ds_read_b32 v60, v60
	v_lshlrev_b32_e32 v97, 16, v17
	s_waitcnt lgkmcnt(1)
	v_fmac_f32_e32 v96, v98, v97
	v_and_b32_e32 v97, 0xffff0000, v17
	s_waitcnt lgkmcnt(0)
	v_fmac_f32_e32 v96, v60, v97
	v_fma_f32 v60, v61, v62, 0
	v_fma_f32 v61, v63, v83, 0
	v_mul_f32_e64 v63, |v96|, s48
	v_exp_f32_e32 v63, v63
	v_fmac_f32_e32 v60, v84, v85
	v_fmac_f32_e32 v60, v88, v89
	v_fmac_f32_e32 v60, v92, v93
	v_add_f32_e32 v63, 1.0, v63
	v_cmp_gt_f32_e32 vcc, s68, v63
	v_fmac_f32_e32 v61, v86, v87
	v_fmac_f32_e32 v61, v90, v91
	v_cndmask_b32_e64 v83, 0, 32, vcc
	v_ldexp_f32 v63, v63, v83
	v_log_f32_e32 v63, v63
	v_min_f32_e32 v62, 0, v96
	v_fmac_f32_e32 v61, v94, v95
	v_mul_f32_e32 v83, 0x3f317217, v63
	v_fma_f32 v83, v63, s42, -v83
	v_fmac_f32_e32 v83, 0x3377d1cf, v63
	v_fmac_f32_e32 v83, 0x3f317217, v63
	v_cmp_lt_f32_e64 s[0:1], |v63|, s78
	s_nop 1
	v_cndmask_b32_e64 v63, v63, v83, s[0:1]
	v_cndmask_b32_e32 v83, 0, v164, vcc
	v_sub_f32_e32 v63, v63, v83
	v_mul_f32_e32 v83, 0xbfb8aa3b, v60
	v_exp_f32_e32 v83, v83
	v_sub_f32_e32 v62, v62, v63
	v_lshl_add_u32 v63, v54, 2, 0
	v_mul_f32_e32 v62, 0x3d800000, v62
	v_add_f32_e32 v83, 1.0, v83
	v_rcp_f32_e32 v83, v83
	v_mul_f32_e32 v62, 0x3fb8aa3b, v62
	v_exp_f32_e32 v62, v62
	v_mul_f32_e32 v60, v60, v83
	ds_write_b32 v63, v60 offset:16384
	v_mul_f32_e32 v60, 0xbfb8aa3b, v61
	v_exp_f32_e32 v60, v60
	s_nop 0
	v_add_f32_e32 v60, 1.0, v60
	v_rcp_f32_e32 v60, v60
	s_nop 0
	v_mul_f32_e32 v60, v61, v60
	v_mul_f32_e32 v60, 0x3e13cd3a, v60
	ds_write2st64_b32 v63, v60, v62 offset1:32

; __device__ __forceinline__ void gl_item_C(const Params& p, int l, int seg, int h, LAS float* sm, int tid, int lane, int wave) {
;     ...
;         bf16_t pf_g1[2], pf_g2[2];
; #pragma unroll
;         for (int rr = 0; rr < 2; ++rr) { const int tok = seg * SEG + sb * TS + wave + 8 * rr; const bf16_t* rowp = PG + (size_t)tok * PGL + 784 + h * 96; pf_g1[rr] = rowp[lane]; pf_g2[rr] = lane < 32 ? rowp[64 + lane] : (bf16_t)0; }
.LBB0_324:
	s_lshl_b32 s27, s65, 4
	s_add_i32 s36, s64, s27
	v_mad_i64_i32 v[50:51], s[0:1], s36, v165, v[38:39]
	global_load_ushort v30, v[50:51], off offset:1568
	v_mov_b32_e32 v48, 0
	v_mov_b32_e32 v32, 0
	s_and_saveexec_b64 s[0:1], s[8:9]
	s_cbranch_execz .LBB0_326
	global_load_ushort v32, v[50:51], off offset:1696
.LBB0_326:
	s_or_b64 exec, exec, s[0:1]
	s_add_i32 s34, s36, 8
	v_mad_i64_i32 v[50:51], s[0:1], s34, v165, v[38:39]
	global_load_ushort v49, v[50:51], off offset:1568
	s_ashr_i32 s37, s36, 31
	s_and_saveexec_b64 s[0:1], s[8:9]
	s_cbranch_execz .LBB0_328
	global_load_ushort v48, v[50:51], off offset:1696

; __device__ __forceinline__ float bf2f(bf16_t b) { return __uint_as_float(((unsigned)b) << 16); }
; __device__ __forceinline__ bf16_t f2bf(float f) { unsigned u = __float_as_uint(f); u += 0x7FFFu + ((u >> 16) & 1u); return (bf16_t)(u >> 16); }
; __device__ __forceinline__ float silu(float x) { return x * __builtin_amdgcn_rcpf(1.0f + __expf(-x)); }
; __device__ __forceinline__ void gl_item_C(const Params& p, int l, int seg, int h, LAS float* sm, int tid, int lane, int wave) {
;     ...
;         for (int rr = 0; rr < 2; ++rr) {
;             const int t = wave + 8 * rr, tok = seg * SEG + sb * TS + t;
;             const float y1 = ob[t * 96 + lane];
;             const float y2 = lane < 32 ? ob[t * 96 + 64 + lane] : 0.f;
;             const float ms = wave_sum(y1 * y1 + y2 * y2) * (1.0f / 96.0f);
;             const float rs = rsqrtf(ms + 1e-5f);
;             bf16_t* mo = MX + (size_t)tok * D + 640 + h * 96;
;             mo[lane] = f2bf(y1 * rs * gn1 * silu(bf2f(pf_g1[rr])));
;             if (lane < 32) mo[64 + lane] = f2bf(y2 * rs * gn2 * silu(bf2f(pf_g2[rr])));
;         }
.LBB0_349:
	s_add_i32 s0, s5, s72
	v_lshl_add_u32 v0, v56, 2, s0
	ds_read_b32 v50, v0 offset:61440
	v_mov_b32_e32 v51, 0
	s_and_saveexec_b64 s[0:1], s[8:9]
	ds_read_b32 v51, v0 offset:61696
	s_or_b64 exec, exec, s[0:1]
	s_waitcnt lgkmcnt(0)
	v_pk_mul_f32 v[52:53], v[50:51], v[50:51]
	s_nop 0
	v_add_f32_e32 v0, v52, v53
	v_mov_b32_e32 v52, 0
	s_nop 0
	v_add_f32_dpp v0, v0, v0 quad_perm:[1,0,3,2] row_mask:0xf bank_mask:0xf bound_ctrl:1
	s_nop 1
	v_add_f32_dpp v0, v0, v0 quad_perm:[2,3,0,1] row_mask:0xf bank_mask:0xf bound_ctrl:1
	s_nop 1
	v_add_f32_dpp v0, v0, v0 row_half_mirror row_mask:0xf bank_mask:0xf bound_ctrl:1
	s_nop 1
	v_add_f32_dpp v0, v0, v0 row_mirror row_mask:0xf bank_mask:0xf bound_ctrl:1
	s_nop 1
	v_mov_b32_dpp v52, v0 row_bcast:15 row_mask:0xa bank_mask:0xf
	v_add_f32_e32 v0, v0, v52
	v_mov_b32_e32 v52, 0
	s_nop 1
	v_mov_b32_dpp v52, v0 row_bcast:31 row_mask:0xc bank_mask:0xf
	v_add_f32_e32 v0, v0, v52
	s_nop 0
	v_readlane_b32 s0, v0, 63
	s_nop 1
	v_fma_f32 v0, s0, v166, v131
	v_mul_f32_e32 v52, 0x4b800000, v0
	v_cmp_gt_f32_e32 vcc, s68, v0
	s_lshl_b64 s[0:1], s[36:37], 11
	s_add_u32 s0, s62, s0
	v_cndmask_b32_e32 v0, v0, v52, vcc
	v_rsq_f32_e32 v0, v0
	s_addc_u32 s1, s63, s1
	s_add_u32 s0, s0, s26
	s_addc_u32 s1, s1, 0
	v_mul_f32_e32 v52, 0x45800000, v0
	v_cndmask_b32_e32 v58, v0, v52, vcc
	s_waitcnt vmcnt(0)
	v_lshlrev_b32_e32 v32, 16, v32
	v_lshlrev_b32_e32 v48, 16, v48
	v_lshlrev_b32_e32 v52, 16, v30
	v_mul_f32_e32 v0, 0xbfb8aa3b, v52
	v_exp_f32_e32 v0, v0
	v_mul_f32_e32 v53, v50, v58
	v_add_f32_e32 v0, 1.0, v0
	v_rcp_f32_e32 v30, v0
	s_nop 0
	v_pk_mul_f32 v[52:53], v[30:31], v[52:53]
	s_nop 0
	v_pk_mul_f32 v[52:53], v[52:53], v[52:53] op_sel:[0,1] op_sel_hi:[1,0]
	s_nop 0
	v_bfe_u32 v0, v52, 16, 1
	v_add3_u32 v30, v52, v0, s61
	v_lshlrev_b32_e32 v0, 1, v56
	v_lshl_add_u64 v[52:53], s[0:1], 0, v[0:1]
	v_add_co_u32_e32 v60, vcc, 0x7780000, v52
	s_nop 1
	v_addc_co_u32_e32 v61, vcc, 0, v53, vcc
	global_store_short_d16_hi v[60:61], v30, off offset:1280
	s_and_saveexec_b64 s[0:1], s[8:9]
	s_cbranch_execz .LBB0_353
	v_mul_f32_e32 v30, 0xbfb8aa3b, v32
	v_exp_f32_e32 v30, v30
	v_mul_f32_e32 v51, v51, v58
	s_mov_b64 s[6:7], 0x7780500
	v_lshl_add_u64 v[52:53], v[52:53], 0, s[6:7]
	v_add_f32_e32 v30, 1.0, v30
	v_rcp_f32_e32 v50, v30
	s_nop 0
	v_pk_mul_f32 v[50:51], v[32:33], v[50:51]
	s_nop 0
	v_pk_mul_f32 v[50:51], v[50:51], v[50:51] op_sel:[0,1] op_sel_hi:[1,0]
	s_nop 0
	v_bfe_u32 v30, v50, 16, 1
	v_add3_u32 v30, v50, v30, s61
	global_store_short_d16_hi v[52:53], v30, off offset:128

.LBB0_570:
	s_or_b64 exec, exec, s[0:1]
	v_ashrrev_i32_e32 v18, 4, v54
	v_add_u32_e32 v29, v18, v24
	s_or_b32 s22, s25, 0x6d
	v_mul_lo_u32 v18, v29, s74
	v_sub_u32_e32 v18, v30, v18
	v_add_u32_e32 v20, s22, v29
	v_ashrrev_i32_e32 v19, 31, v18
	v_cmp_lt_i32_e32 vcc, -1, v20
	v_mov_b32_e32 v37, 0
	v_mov_b32_e32 v40, 0
	s_and_saveexec_b64 s[0:1], vcc
	s_cbranch_execz .LBB0_572
	v_mov_b64_e32 v[22:23], s[20:21]
	v_mad_u64_u32 v[22:23], s[36:37], v20, s69, v[22:23]
	s_lshl_b32 s72, s24, 1
	v_lshl_add_u64 v[22:23], v[22:23], 0, s[72:73]
	v_lshl_add_u64 v[22:23], v[18:19], 1, v[22:23]
	global_load_ushort v40, v[22:23], off offset:768
.LBB0_572:
	s_or_b64 exec, exec, s[0:1]
	v_cmp_lt_i32_e32 vcc, -2, v20
	s_and_saveexec_b64 s[0:1], vcc
	s_cbranch_execz .LBB0_574
	v_add_u32_e32 v21, 1, v20
	v_mov_b64_e32 v[22:23], s[20:21]
	v_mad_u64_u32 v[22:23], s[36:37], v21, s69, v[22:23]
	s_lshl_b32 s72, s24, 1
	v_lshl_add_u64 v[22:23], v[22:23], 0, s[72:73]
	v_lshl_add_u64 v[22:23], v[18:19], 1, v[22:23]
	global_load_ushort v37, v[22:23], off offset:768
.LBB0_574:
	s_or_b64 exec, exec, s[0:1]
	v_cmp_lt_i32_e32 vcc, -3, v20
	v_mov_b32_e32 v36, 0
	v_mov_b32_e32 v44, 0
	s_and_saveexec_b64 s[0:1], vcc
	s_cbranch_execz .LBB0_576
	v_add_u32_e32 v21, 2, v20
	v_mov_b64_e32 v[22:23], s[20:21]
	v_mad_u64_u32 v[22:23], s[36:37], v21, s69, v[22:23]
	s_lshl_b32 s72, s24, 1
	v_lshl_add_u64 v[22:23], v[22:23], 0, s[72:73]
	v_lshl_add_u64 v[22:23], v[18:19], 1, v[22:23]
	global_load_ushort v44, v[22:23], off offset:768
.LBB0_576:
	s_or_b64 exec, exec, s[0:1]
	v_cmp_lt_i32_e32 vcc, -4, v20
	s_and_saveexec_b64 s[0:1], vcc
	s_cbranch_execz .LBB0_578
	v_add_u32_e32 v22, 3, v20
	v_mov_b64_e32 v[20:21], s[20:21]
	v_mad_u64_u32 v[20:21], s[36:37], v22, s69, v[20:21]
	s_lshl_b32 s72, s24, 1
	v_lshl_add_u64 v[20:21], v[20:21], 0, s[72:73]
	v_lshl_add_u64 v[20:21], v[18:19], 1, v[20:21]
	global_load_ushort v36, v[20:21], off offset:768
.LBB0_578:
	s_or_b64 exec, exec, s[0:1]
	v_ashrrev_i32_e32 v20, 4, v53
	v_add_u32_e32 v34, v20, v27
	v_mul_lo_u32 v20, v34, s74
	v_sub_u32_e32 v20, v26, v20
	v_add_u32_e32 v22, s22, v34
	v_ashrrev_i32_e32 v21, 31, v20
	v_cmp_lt_i32_e32 vcc, -1, v22
	v_mov_b32_e32 v41, 0
	v_mov_b32_e32 v43, 0
	s_and_saveexec_b64 s[0:1], vcc
	s_cbranch_execz .LBB0_580
	v_mov_b64_e32 v[38:39], s[20:21]
	v_mad_u64_u32 v[38:39], s[36:37], v22, s69, v[38:39]
	s_lshl_b32 s72, s24, 1
	v_lshl_add_u64 v[38:39], v[38:39], 0, s[72:73]
	v_lshl_add_u64 v[38:39], v[20:21], 1, v[38:39]
	global_load_ushort v43, v[38:39], off offset:768
.LBB0_580:
	s_or_b64 exec, exec, s[0:1]
	v_cmp_lt_i32_e32 vcc, -2, v22
	s_and_saveexec_b64 s[0:1], vcc
	s_cbranch_execz .LBB0_582
	v_add_u32_e32 v23, 1, v22
	v_mov_b64_e32 v[38:39], s[20:21]
	v_mad_u64_u32 v[38:39], s[36:37], v23, s69, v[38:39]
	s_lshl_b32 s72, s24, 1
	v_lshl_add_u64 v[38:39], v[38:39], 0, s[72:73]
	v_lshl_add_u64 v[38:39], v[20:21], 1, v[38:39]
	global_load_ushort v41, v[38:39], off offset:768
.LBB0_582:
	s_or_b64 exec, exec, s[0:1]
	v_cmp_lt_i32_e32 vcc, -3, v22
	v_mov_b32_e32 v39, 0
	v_mov_b32_e32 v61, 0
	s_and_saveexec_b64 s[0:1], vcc
	s_cbranch_execz .LBB0_584
	v_add_u32_e32 v23, 2, v22
	v_mov_b64_e32 v[56:57], s[20:21]
	v_mad_u64_u32 v[56:57], s[36:37], v23, s69, v[56:57]
	s_lshl_b32 s72, s24, 1
	v_lshl_add_u64 v[56:57], v[56:57], 0, s[72:73]
	v_lshl_add_u64 v[56:57], v[20:21], 1, v[56:57]
	global_load_ushort v61, v[56:57], off offset:768
.LBB0_584:
	s_or_b64 exec, exec, s[0:1]
	v_cmp_lt_i32_e32 vcc, -4, v22
	s_and_saveexec_b64 s[0:1], vcc
	s_cbranch_execz .LBB0_586
	v_add_u32_e32 v35, 3, v22
	v_mov_b64_e32 v[22:23], s[20:21]
	v_mad_u64_u32 v[22:23], s[36:37], v35, s69, v[22:23]
	s_lshl_b32 s72, s24, 1
	v_lshl_add_u64 v[22:23], v[22:23], 0, s[72:73]
	v_lshl_add_u64 v[22:23], v[20:21], 1, v[22:23]
	global_load_ushort v39, v[22:23], off offset:768
.LBB0_586:
	s_or_b64 exec, exec, s[0:1]
	v_add_u32_e32 v22, 0x400, v30
	v_mul_hi_i32 v23, v22, s87
	v_lshrrev_b32_e32 v35, 31, v23
	v_ashrrev_i32_e32 v23, 4, v23
	v_add_u32_e32 v35, v23, v35
	v_mul_lo_u32 v23, v35, s74
	v_sub_u32_e32 v22, v22, v23
	v_add_u32_e32 v55, s22, v35
	v_ashrrev_i32_e32 v23, 31, v22
	v_cmp_lt_i32_e32 vcc, -1, v55
	v_mov_b32_e32 v42, 0
	v_mov_b32_e32 v45, 0
	s_and_saveexec_b64 s[0:1], vcc
	s_cbranch_execz .LBB0_588
	v_mov_b64_e32 v[56:57], s[20:21]
	v_mad_u64_u32 v[56:57], s[22:23], v55, s69, v[56:57]
	s_lshl_b32 s72, s24, 1
	v_lshl_add_u64 v[56:57], v[56:57], 0, s[72:73]
	v_lshl_add_u64 v[56:57], v[22:23], 1, v[56:57]
	global_load_ushort v45, v[56:57], off offset:768
.LBB0_588:
	s_or_b64 exec, exec, s[0:1]
	v_cmp_lt_i32_e32 vcc, -2, v55
	s_and_saveexec_b64 s[0:1], vcc
	s_cbranch_execz .LBB0_590
	v_add_u32_e32 v38, 1, v55
	v_mov_b64_e32 v[56:57], s[20:21]
	v_mad_u64_u32 v[56:57], s[22:23], v38, s69, v[56:57]
	s_lshl_b32 s72, s24, 1
	v_lshl_add_u64 v[56:57], v[56:57], 0, s[72:73]
	v_lshl_add_u64 v[56:57], v[22:23], 1, v[56:57]
	global_load_ushort v42, v[56:57], off offset:768
.LBB0_590:
	s_or_b64 exec, exec, s[0:1]
	v_cmp_lt_i32_e32 vcc, -3, v55
	v_mov_b32_e32 v38, 0
	v_mov_b32_e32 v65, 0
	s_and_saveexec_b64 s[0:1], vcc
	s_cbranch_execz .LBB0_592
	v_add_u32_e32 v58, 2, v55
	v_mov_b64_e32 v[56:57], s[20:21]
	v_mad_u64_u32 v[56:57], s[22:23], v58, s69, v[56:57]
	s_lshl_b32 s72, s24, 1
	v_lshl_add_u64 v[56:57], v[56:57], 0, s[72:73]
	v_lshl_add_u64 v[56:57], v[22:23], 1, v[56:57]
	global_load_ushort v65, v[56:57], off offset:768

.LBB0_594:
	s_or_b64 exec, exec, s[0:1]
	s_waitcnt vmcnt(0)
	v_lshlrev_b32_e32 v40, 16, v40
	v_lshlrev_b32_e32 v37, 16, v37
	v_lshlrev_b32_e32 v44, 16, v44
	v_lshlrev_b32_e32 v36, 16, v36
	v_lshlrev_b32_e32 v43, 16, v43
	v_lshlrev_b32_e32 v41, 16, v41
	v_lshlrev_b32_e32 v61, 16, v61
	v_lshlrev_b32_e32 v39, 16, v39
	v_lshlrev_b32_e32 v45, 16, v45
	v_lshlrev_b32_e32 v42, 16, v42
	v_lshlrev_b32_e32 v65, 16, v65
	v_lshlrev_b32_e32 v38, 16, v38
	s_waitcnt lgkmcnt(0)
	s_barrier
	s_and_saveexec_b64 s[22:23], s[10:11]
	s_cbranch_execz .LBB0_596
	v_lshrrev_b32_e32 v54, 3, v54
	v_add_u32_e32 v54, v54, v24
	v_mul_lo_u32 v54, v54, 48
	v_sub_u32_e32 v54, v30, v54
	v_lshl_add_u32 v54, v54, 2, 0
	v_add_u32_e32 v55, 0x12ec0, v54
	v_add_u32_e32 v57, 0x131c0, v54
	v_add_u32_e32 v59, 0x134c0, v54
	v_add_u32_e32 v62, 0x137c0, v54
	v_add_u32_e32 v64, 0x13a00, v54
	v_add_u32_e32 v67, 0x12200, v54
	ds_read_b32 v55, v55
	ds_read_b32 v57, v57
	ds_read_b32 v59, v59
	ds_read_b32 v62, v62
	ds_read_b32 v64, v64
	ds_read_b32 v67, v67
	v_lshlrev_b32_e32 v66, 16, v14
	v_lshlrev_b32_e32 v56, 16, v50
	v_lshlrev_b32_e32 v58, 16, v49
	v_lshlrev_b32_e32 v60, 16, v52
	s_waitcnt lgkmcnt(0)
	v_fmac_f32_e32 v64, v67, v66
	v_add_u32_e32 v67, 0x122c0, v54
	ds_read_b32 v67, v67
	v_and_b32_e32 v66, 0xffff0000, v14
	v_lshlrev_b32_e32 v63, 16, v47
	s_waitcnt lgkmcnt(0)
	v_fmac_f32_e32 v64, v67, v66
	v_add_u32_e32 v67, 0x12380, v54
	ds_read_b32 v67, v67
	v_lshlrev_b32_e32 v66, 16, v15
	s_waitcnt lgkmcnt(0)
	v_fmac_f32_e32 v64, v67, v66
	v_add_u32_e32 v67, 0x12440, v54
	ds_read_b32 v67, v67
	v_and_b32_e32 v66, 0xffff0000, v15
	s_waitcnt lgkmcnt(0)
	v_fmac_f32_e32 v64, v67, v66
	v_add_u32_e32 v67, 0x12500, v54
	ds_read_b32 v67, v67
	v_lshlrev_b32_e32 v66, 16, v16
	s_waitcnt lgkmcnt(0)
	v_fmac_f32_e32 v64, v67, v66
	v_add_u32_e32 v67, 0x125c0, v54
	ds_read_b32 v67, v67
	v_and_b32_e32 v66, 0xffff0000, v16
	s_waitcnt lgkmcnt(0)
	v_fmac_f32_e32 v64, v67, v66
	v_add_u32_e32 v67, 0x12680, v54
	ds_read_b32 v67, v67
	v_lshlrev_b32_e32 v66, 16, v17
	s_waitcnt lgkmcnt(0)
	v_fmac_f32_e32 v64, v67, v66
	v_add_u32_e32 v67, 0x12740, v54
	ds_read_b32 v67, v67
	v_and_b32_e32 v66, 0xffff0000, v17
	s_waitcnt lgkmcnt(0)
	v_fmac_f32_e32 v64, v67, v66
	v_add_u32_e32 v67, 0x12800, v54
	ds_read_b32 v67, v67
	v_lshlrev_b32_e32 v66, 16, v6
	s_waitcnt lgkmcnt(0)
	v_fmac_f32_e32 v64, v67, v66
	v_add_u32_e32 v67, 0x128c0, v54
	ds_read_b32 v67, v67
	v_and_b32_e32 v66, 0xffff0000, v6
	s_waitcnt lgkmcnt(0)
	v_fmac_f32_e32 v64, v67, v66
	v_add_u32_e32 v67, 0x12980, v54
	ds_read_b32 v67, v67
	v_lshlrev_b32_e32 v66, 16, v7
	s_waitcnt lgkmcnt(0)
	v_fmac_f32_e32 v64, v67, v66
	v_add_u32_e32 v67, 0x12a40, v54
	ds_read_b32 v67, v67
	v_and_b32_e32 v66, 0xffff0000, v7
	s_waitcnt lgkmcnt(0)
	v_fmac_f32_e32 v64, v67, v66
	v_add_u32_e32 v67, 0x12b00, v54
	ds_read_b32 v67, v67
	v_lshlrev_b32_e32 v66, 16, v8
	s_waitcnt lgkmcnt(0)
	v_fmac_f32_e32 v64, v67, v66
	v_add_u32_e32 v67, 0x12bc0, v54
	ds_read_b32 v67, v67
	v_and_b32_e32 v66, 0xffff0000, v8
	s_waitcnt lgkmcnt(0)
	v_fmac_f32_e32 v64, v67, v66
	v_add_u32_e32 v67, 0x12c80, v54
	ds_read_b32 v67, v67
	v_add_u32_e32 v54, 0x12d40, v54
	ds_read_b32 v54, v54
	v_lshlrev_b32_e32 v66, 16, v9
	s_waitcnt lgkmcnt(1)
	v_fmac_f32_e32 v64, v67, v66
	v_and_b32_e32 v66, 0xffff0000, v9
	s_waitcnt lgkmcnt(0)
	v_fmac_f32_e32 v64, v54, v66
	v_fma_f32 v54, v55, v56, 0
	v_mul_f32_e64 v56, |v64|, s48
	v_exp_f32_e32 v56, v56
	v_fmac_f32_e32 v54, v57, v58
	v_fmac_f32_e32 v54, v59, v60
	v_fmac_f32_e32 v54, v62, v63
	v_add_f32_e32 v56, 1.0, v56
	v_cmp_gt_f32_e32 vcc, s68, v56
	v_min_f32_e32 v55, 0, v64
	s_nop 0
	v_cndmask_b32_e64 v57, 0, 32, vcc
	v_ldexp_f32 v56, v56, v57
	v_log_f32_e32 v56, v56
	s_nop 0
	v_mul_f32_e32 v57, 0x3f317217, v56
	v_fma_f32 v57, v56, s42, -v57
	v_fmac_f32_e32 v57, 0x3377d1cf, v56
	v_fmac_f32_e32 v57, 0x3f317217, v56
	v_cmp_lt_f32_e64 s[0:1], |v56|, s78
	s_nop 1
	v_cndmask_b32_e64 v56, v56, v57, s[0:1]
	v_cndmask_b32_e32 v57, 0, v164, vcc
	v_sub_f32_e32 v56, v56, v57
	v_mul_f32_e32 v57, 0xbfb8aa3b, v54
	v_exp_f32_e32 v57, v57
	v_sub_f32_e32 v55, v55, v56
	v_mul_f32_e32 v55, 0x3d800000, v55
	v_mul_f32_e32 v55, 0x3fb8aa3b, v55
	v_add_f32_e32 v57, 1.0, v57
	v_rcp_f32_e32 v57, v57
	v_exp_f32_e32 v55, v55
	v_lshl_add_u32 v56, v30, 2, 0
	v_mul_f32_e32 v54, v54, v57
	ds_write2st64_b32 v56, v55, v54 offset0:152 offset1:184

; __device__ __forceinline__ void lds_barrier() { asm volatile("s_waitcnt lgkmcnt(0)" ::: "memory"); __builtin_amdgcn_s_barrier(); asm volatile("" ::: "memory"); }
; template <bool HG>
; __device__ __forceinline__ void diag_item_A(const Params& p, int l, int seg, int h, LAS float* sm, int tid, int lane, int wave) {
;     ...
;     DG_LOAD(7);
;     lds_barrier();
;     DG_STORE(1); DG_LOAD(6);
.LBB0_717:
	s_or_b64 exec, exec, s[0:1]
	s_add_i32 s72, s18, 0xfffffd00
	s_add_u32 s10, s14, 0x9780000
	s_addc_u32 s11, s15, 0
	s_lshl_b32 s0, s72, 5
	s_and_b32 s1, s27, 0x7fffff80
	s_or_b32 s22, s0, 0x70
	s_lshl_b32 s12, s30, 7
	s_lshl_b32 s13, s30, 8
	s_add_u32 s20, s10, s13
	v_and_b32_e32 v4, 0x7f, v30
	s_addc_u32 s21, s11, 0
	v_lshlrev_b32_e32 v0, 1, v4
	v_ashrrev_i32_e32 v10, 7, v30
	s_waitcnt vmcnt(0)
	v_lshl_add_u64 v[18:19], s[20:21], 0, v[0:1]
	v_add_u32_e32 v0, s22, v10
	v_mad_i64_i32 v[2:3], s[20:21], v0, s79, v[18:19]
	global_load_ushort v11, v[2:3], off offset:1024
	v_add_u32_e32 v12, 0x200, v30
	v_ashrrev_i32_e32 v13, 7, v12
	v_add_u32_e32 v0, s22, v13
	v_mad_i64_i32 v[2:3], s[20:21], v0, s79, v[18:19]
	global_load_ushort v14, v[2:3], off offset:1024
	v_add_u32_e32 v0, 0x400, v30
	v_ashrrev_i32_e32 v16, 7, v0
	v_add_u32_e32 v2, 0x600, v30
	v_add_u32_e32 v0, s22, v16
	v_ashrrev_i32_e32 v17, 7, v2
	v_mad_i64_i32 v[2:3], s[20:21], v0, s79, v[18:19]
	global_load_ushort v20, v[2:3], off offset:1024
	v_add_u32_e32 v8, s22, v17
	v_mad_i64_i32 v[8:9], s[20:21], v8, s79, v[18:19]
	global_load_ushort v23, v[8:9], off offset:1024
	v_ashrrev_i32_e32 v15, 6, v30
	v_ashrrev_i32_e32 v22, 6, v12
	v_mov_b64_e32 v[2:3], s[10:11]
	v_add_u32_e32 v0, s22, v15
	s_mov_b32 s13, s73
	v_lshl_add_u32 v21, v4, 2, 0
	v_add_u32_e32 v6, s22, v22
	v_mad_i64_i32 v[4:5], s[20:21], v0, s79, v[2:3]
	v_mad_i64_i32 v[6:7], s[20:21], v6, s79, v[2:3]
	v_lshl_add_u64 v[4:5], v[4:5], 0, s[12:13]
	v_lshlrev_b32_e32 v0, 1, v46
	v_lshl_add_u64 v[6:7], v[6:7], 0, s[12:13]
	v_lshl_add_u64 v[4:5], v[4:5], 0, v[0:1]
	v_lshl_add_u64 v[6:7], v[6:7], 0, v[0:1]
	global_load_ushort v26, v[4:5], off offset:2048
	global_load_ushort v27, v[6:7], off offset:2048
	s_or_b32 s0, s0, 0x60
	v_add_u32_e32 v8, s0, v15
	v_add_u32_e32 v25, s0, v22
	v_mad_i64_i32 v[8:9], s[20:21], v8, s79, v[2:3]
	v_mad_i64_i32 v[2:3], s[20:21], v25, s79, v[2:3]
	v_lshl_add_u64 v[4:5], v[8:9], 0, s[12:13]
	s_waitcnt lgkmcnt(0)
	s_barrier
	v_lshl_add_u64 v[2:3], v[2:3], 0, s[12:13]
	v_lshl_add_u64 v[4:5], v[4:5], 0, v[0:1]
	v_lshl_add_u64 v[2:3], v[2:3], 0, v[0:1]
	global_load_ushort v28, v[4:5], off offset:2048
	global_load_ushort v29, v[2:3], off offset:2048
	v_add_u32_e32 v2, s0, v10
	v_add_u32_e32 v4, s0, v13
	v_add_u32_e32 v35, 0x12000, v21
	v_add_u32_e32 v6, s0, v16
	v_add_u32_e32 v8, s0, v17
	v_mad_i64_i32 v[2:3], s[20:21], v2, s79, v[18:19]
	v_mad_i64_i32 v[4:5], s[20:21], v4, s79, v[18:19]
	v_mad_i64_i32 v[6:7], s[20:21], v6, s79, v[18:19]
	v_mad_i64_i32 v[8:9], s[20:21], v8, s79, v[18:19]
	ds_read_b32 v21, v35
	global_load_ushort v2, v[2:3], off offset:1024
	s_nop 0
	global_load_ushort v3, v[4:5], off offset:1024
	s_nop 0
	global_load_ushort v4, v[6:7], off offset:1024
	global_load_ushort v5, v[8:9], off offset:1024
	v_and_b32_e32 v25, 15, v30
	s_lshl_b32 s0, s19, 4
	s_add_i32 s13, 0, 0x14000
	s_waitcnt lgkmcnt(0)
	v_sub_f32_e32 v6, 1.0, v21
	v_readlane_b32 s2, v254, 5
	s_add_u32 s10, s10, s12
	s_addc_u32 s11, s11, 0
	v_mul_lo_u32 v36, v30, s96
	s_mov_b32 s12, 0
	s_waitcnt vmcnt(11)
	v_lshlrev_b32_e32 v11, 16, v11
	v_mul_f32_e32 v11, 0xbfb8aa3b, v11
	v_exp_f32_e32 v11, v11
	s_waitcnt vmcnt(10)
	v_lshlrev_b32_e32 v8, 16, v14
	v_add_f32_e32 v7, 1.0, v11
	v_rcp_f32_e32 v7, v7
	v_mul_f32_e32 v8, 0xbfb8aa3b, v8
	v_exp_f32_e32 v8, v8
	v_fmac_f32_e32 v21, v7, v6
	v_sub_f32_e32 v7, 1.0, v7
	v_max_f32_e32 v9, 0xda24260, v21
	v_mul_f32_e32 v6, v7, v6
	ds_write_b32 v24, v9 offset:38912
	ds_write_b32 v24, v6 offset:47104
	ds_read_b32 v7, v35
	v_add_f32_e32 v6, 1.0, v8
	v_rcp_f32_e32 v6, v6
	s_waitcnt lgkmcnt(0)
	v_sub_f32_e32 v9, 1.0, v7
	v_fmac_f32_e32 v7, v6, v9
	v_sub_f32_e32 v8, 1.0, v6
	v_max_f32_e32 v6, 0xda24260, v7
	ds_write_b32 v24, v6 offset:40960
	s_waitcnt vmcnt(9)
	v_lshlrev_b32_e32 v6, 16, v20
	v_mul_f32_e32 v6, 0xbfb8aa3b, v6
	v_exp_f32_e32 v6, v6
	v_mul_f32_e32 v7, v8, v9
	ds_write_b32 v24, v7 offset:49152
	ds_read_b32 v7, v35
	v_add_f32_e32 v6, 1.0, v6
	v_rcp_f32_e32 v6, v6
	v_lshl_add_u64 v[20:21], s[10:11], 0, v[0:1]
	v_add_u32_e32 v0, s1, v22
	s_waitcnt lgkmcnt(0)
	v_sub_f32_e32 v8, 1.0, v7
	v_fmac_f32_e32 v7, v6, v8
	v_max_f32_e32 v7, 0xda24260, v7
	ds_write_b32 v24, v7 offset:43008
	s_waitcnt vmcnt(8)
	v_lshlrev_b32_e32 v7, 16, v23
	v_mul_f32_e32 v7, 0xbfb8aa3b, v7
	v_sub_f32_e32 v6, 1.0, v6
	v_exp_f32_e32 v7, v7
	v_mul_f32_e32 v6, v6, v8
	ds_write_b32 v24, v6 offset:51200
	ds_read_b32 v6, v35
	v_add_f32_e32 v7, 1.0, v7
	v_rcp_f32_e32 v7, v7
	s_waitcnt vmcnt(4)
	v_perm_b32 v50, v29, v28, s47
	v_add_u32_e32 v37, 0x50, v0
	s_waitcnt lgkmcnt(0)
	v_sub_f32_e32 v8, 1.0, v6
	v_fmac_f32_e32 v6, v7, v8
	v_max_f32_e32 v6, 0xda24260, v6
	ds_write_b32 v24, v6 offset:45056
	v_sub_f32_e32 v6, 1.0, v7
	v_mul_f32_e32 v6, v6, v8
	v_lshlrev_b32_e32 v7, 16, v26
	ds_write2st64_b32 v24, v6, v7 offset0:208 offset1:216
	v_lshlrev_b32_e32 v6, 16, v27
	ds_write_b32 v24, v6 offset:57344
	v_or_b32_e32 v6, s0, v25
	v_mul_lo_u32 v6, v6, s96
	v_and_b32_e32 v7, 48, v46
	v_add3_u32 v27, s13, v6, v7
	v_add_u32_e32 v6, s2, v7
	v_lshrrev_b32_e32 v7, 26, v31
	v_add_u32_e32 v7, v30, v7
	v_ashrrev_i32_e32 v8, 6, v7
	v_and_b32_e32 v7, 0xfffffc0, v7
	v_sub_u32_e32 v7, v30, v7
	v_mul_lo_u32 v7, v7, s96
	v_lshlrev_b32_e32 v8, 1, v8
	v_add3_u32 v29, s2, v7, v8
	v_ashrrev_i32_e32 v7, 31, v12
	v_lshrrev_b32_e32 v7, 26, v7
	v_add_u32_e32 v7, v12, v7
	v_ashrrev_i32_e32 v8, 6, v7
	v_and_b32_e32 v7, 0xfffffc0, v7
	v_add_u32_e32 v0, s1, v15
	v_sub_u32_e32 v7, v12, v7
	v_add_u32_e32 v38, 0x50, v0
	v_add_u32_e32 v0, s1, v17
	v_mul_lo_u32 v7, v7, s96
	v_lshlrev_b32_e32 v8, 1, v8
	v_add_u32_e32 v39, 0x50, v0
	v_add_u32_e32 v0, s1, v16
	s_waitcnt lgkmcnt(0)
	s_barrier
	v_add3_u32 v28, s2, v7, v8
	v_or_b32_e32 v8, 48, v46
	v_add_u32_e32 v40, 0x50, v0
	v_add_u32_e32 v0, s1, v13
	v_mul_u32_u24_e32 v7, 0x50, v25
	v_mul_u32_u24_e32 v8, 0x50, v8
	s_waitcnt vmcnt(2)
	v_perm_b32 v52, v3, v2, s47
	v_add_u32_e32 v41, 0x50, v0
	v_add_u32_e32 v0, s1, v10
	v_mov_b32_e32 v2, 0
	v_lshrrev_b32_e32 v26, 4, v46
	s_waitcnt vmcnt(0)
	v_perm_b32 v51, v5, v4, s47
	v_and_b32_e32 v246, 0xffff, v52
	v_lshrrev_b32_e32 v247, 16, v52
	v_and_b32_e32 v250, 0xffff, v50
	v_lshrrev_b32_e32 v251, 16, v50
	v_and_b32_e32 v248, 0xffff, v51
	v_lshrrev_b32_e32 v249, 16, v51
	v_add_u32_e32 v42, 0x50, v0
	v_mov_b32_e32 v23, 1.0
	s_mov_b32 s1, 0
	v_add_u32_e32 v34, v6, v7
	v_add_u32_e32 v0, v6, v8
	v_mov_b32_e32 v3, v2
	v_mov_b32_e32 v4, v2
	v_mov_b32_e32 v5, v2
	v_mov_b32_e32 v6, v2
	v_mov_b32_e32 v7, v2
	v_mov_b32_e32 v8, v2
	v_mov_b32_e32 v9, v2
	v_mov_b32_e32 v10, v2
	v_mov_b32_e32 v11, v2
	v_mov_b32_e32 v12, v2
	v_mov_b32_e32 v13, v2
	v_mov_b32_e32 v14, v2
	v_mov_b32_e32 v15, v2
	v_mov_b32_e32 v16, v2
	v_mov_b32_e32 v17, v2
	s_branch .LBB0_719
; #define LAS __attribute__((address_space(3)))
; __device__ __forceinline__ bf16_t f2bf(float f) { unsigned u = __float_as_uint(f); u += 0x7FFFu + ((u >> 16) & 1u); return (bf16_t)(u >> 16); }
; __device__ __forceinline__ void lds_barrier() { asm volatile("s_waitcnt lgkmcnt(0)" ::: "memory"); __builtin_amdgcn_s_barrier(); asm volatile("" ::: "memory"); }
; template <bool HG>
; __device__ __forceinline__ void diag_item_A(const Params& p, int l, int seg, int h, LAS float* sm, int tid, int lane, int wave) {
;     ...
;     for (int sbi = 0; sbi < SEG / TS; ++sbi) {
;         const int sb = SEG / TS - 1 - sbi, cur = sb & 1;
;         const LAS float* bf = sm + cur * 7680;
;         if (tid < K) {
;             float dd[TS], kk_[TS];
; #pragma unroll
;             for (int t = 0; t < TS; ++t) { dd[t] = bf[2048 + t * K + tid]; kk_[t] = bf[4096 + t * K + tid]; }
; #pragma unroll
;             for (int t = TS - 1; t >= 0; --t) { kT[tid * TP + t] = f2bf(kk_[t] * R); R *= dd[t]; }
;         }
;         { float vv_[EV];
; #pragma unroll
;           for (int e = 0; e < EV; ++e) vv_[e] = bf[6144 + tid + 512 * e];
; #pragma unroll
;           for (int e = 0; e < EV; ++e) { const int idx = tid + 512 * e; vT[(idx % V) * TP + (idx / V)] = f2bf(vv_[e]); } }
;         lds_barrier();
;         if (HG) {
;             const pg8::bf16x8 a = *(const LAS pg8::bf16x8*)(kT + (16 * wave + row) * TP + 8 * q);
; #pragma unroll
;             for (int n = 0; n < 4; ++n) acc[n] = __builtin_amdgcn_mfma_f32_16x16x32_bf16(a, *(const LAS pg8::bf16x8*)(vT + (16 * n + row) * TP + 8 * q), acc[n], 0, 0, 0);
;         } else if (wave < 6) {
;             const pg8::bf16x8 b = *(const LAS pg8::bf16x8*)(vT + (16 * wave + row) * TP + 8 * q);
; #pragma unroll
;             for (int m = 0; m < 3; ++m) acc[m] = __builtin_amdgcn_mfma_f32_16x16x32_bf16(*(const LAS pg8::bf16x8*)(kT + (16 * m + row) * TP + 8 * q), b, acc[m], 0, 0, 0);
;         }
;         if (sbi + 1 < SEG / TS) DG_STORE(cur ^ 1);
;         if (sbi + 2 < SEG / TS) DG_LOAD(sb - 2);
;         lds_barrier();
.LBB0_718:
	s_or_b64 exec, exec, s[10:11]
	ds_read2st64_b32 v[44:45], v43 offset0:96 offset1:104
	s_waitcnt vmcnt(0)
	v_perm_b32 v52, v247, v246, s47
	v_perm_b32 v51, v249, v248, s47
	v_perm_b32 v50, v251, v250, s47
	v_lshlrev_b32_e32 v43, 16, v52
	v_mul_f32_e32 v43, 0xbfb8aa3b, v43
	v_exp_f32_e32 v43, v43
	s_mulk_i32 s13, 0x7800
	s_waitcnt lgkmcnt(0)
	v_bfe_u32 v22, v44, 16, 1
	v_add3_u32 v22, v44, v22, s61
	ds_write_b16_d16_hi v29, v22
	v_bfe_u32 v22, v45, 16, 1
	v_add3_u32 v22, v45, v22, s61
	ds_write_b16_d16_hi v28, v22
	s_waitcnt lgkmcnt(0)
	s_barrier
	ds_read_b128 v[54:57], v27
	ds_read_b128 v[58:61], v34
	v_add_f32_e32 v43, 1.0, v43
	s_waitcnt lgkmcnt(0)
	v_mfma_f32_16x16x32_bf16 v[6:9], v[54:57], v[58:61], v[6:9]
	ds_read_b128 v[58:61], v34 offset:1280
	v_rcp_f32_e32 v43, v43
	v_add_u32_e32 v22, s13, v24
	s_waitcnt lgkmcnt(0)
	v_mfma_f32_16x16x32_bf16 v[10:13], v[54:57], v[58:61], v[10:13]
	ds_read_b128 v[58:61], v34 offset:2560
	ds_read_b32 v44, v35
	s_add_i32 s12, s12, 1
	s_waitcnt lgkmcnt(1)
	v_mfma_f32_16x16x32_bf16 v[14:17], v[54:57], v[58:61], v[14:17]
	ds_read_b128 v[58:61], v0
	s_waitcnt lgkmcnt(1)
	v_sub_f32_e32 v45, 1.0, v44
	v_fmac_f32_e32 v44, v43, v45
	v_sub_f32_e32 v43, 1.0, v43
	v_mul_f32_e32 v43, v43, v45
	ds_write_b32 v22, v43 offset:16384
	v_and_b32_e32 v43, 0xffff0000, v52
	v_mul_f32_e32 v43, 0xbfb8aa3b, v43
	v_exp_f32_e32 v43, v43
	v_max_f32_e32 v44, 0xda24260, v44
	ds_write_b32 v22, v44 offset:8192
	ds_read_b32 v44, v35
	v_add_f32_e32 v43, 1.0, v43
	v_rcp_f32_e32 v43, v43
	s_waitcnt lgkmcnt(3)
	v_mfma_f32_16x16x32_bf16 v[2:5], v[54:57], v[58:61], v[2:5]
	s_waitcnt lgkmcnt(0)
	v_sub_f32_e32 v45, 1.0, v44
	v_fmac_f32_e32 v44, v43, v45
	v_sub_f32_e32 v43, 1.0, v43
	v_mul_f32_e32 v43, v43, v45
	ds_write_b32 v22, v43 offset:18432
	v_lshlrev_b32_e32 v43, 16, v51
	v_mul_f32_e32 v43, 0xbfb8aa3b, v43
	v_exp_f32_e32 v43, v43
	v_max_f32_e32 v44, 0xda24260, v44
	ds_write_b32 v22, v44 offset:10240
	ds_read_b32 v44, v35
	v_add_f32_e32 v43, 1.0, v43
	v_rcp_f32_e32 v43, v43
	s_waitcnt lgkmcnt(0)
	v_sub_f32_e32 v45, 1.0, v44
	v_fmac_f32_e32 v44, v43, v45
	v_sub_f32_e32 v43, 1.0, v43
	v_mul_f32_e32 v43, v43, v45
	ds_write_b32 v22, v43 offset:20480
	v_and_b32_e32 v43, 0xffff0000, v51
	v_mul_f32_e32 v43, 0xbfb8aa3b, v43
	v_exp_f32_e32 v43, v43
	v_max_f32_e32 v44, 0xda24260, v44
	ds_write_b32 v22, v44 offset:12288
	ds_read_b32 v44, v35
	v_add_f32_e32 v43, 1.0, v43
	v_rcp_f32_e32 v43, v43
	s_waitcnt lgkmcnt(0)
	v_sub_f32_e32 v45, 1.0, v44
	v_fmac_f32_e32 v44, v43, v45
	v_max_f32_e32 v44, 0xda24260, v44
	v_sub_f32_e32 v43, 1.0, v43
	ds_write_b32 v22, v44 offset:14336
	v_mul_f32_e32 v43, v43, v45
	v_lshlrev_b32_e32 v44, 16, v50
	ds_write2st64_b32 v22, v43, v44 offset0:88 offset1:96
	v_and_b32_e32 v43, 0xffff0000, v50
	ds_write_b32 v22, v43 offset:26624
	v_add_u32_e32 v22, s1, v42
	v_mad_i64_i32 v[44:45], s[10:11], v22, s79, v[18:19]
	v_add_u32_e32 v22, s1, v41
	global_load_ushort v246, v[44:45], off offset:1024
	v_mad_i64_i32 v[44:45], s[10:11], v22, s79, v[18:19]
	v_add_u32_e32 v22, s1, v40
	global_load_ushort v247, v[44:45], off offset:1024
	v_mad_i64_i32 v[44:45], s[10:11], v22, s79, v[18:19]
	v_add_u32_e32 v22, s1, v39
	global_load_ushort v248, v[44:45], off offset:1024
	v_mad_i64_i32 v[44:45], s[10:11], v22, s79, v[18:19]
	v_add_u32_e32 v22, s1, v38
	v_mad_i64_i32 v[50:51], s[10:11], v22, s79, v[20:21]
	v_add_u32_e32 v22, s1, v37
	global_load_ushort v249, v[44:45], off offset:1024
	s_add_i32 s1, s1, -16
	global_load_ushort v250, v[50:51], off offset:2048
	v_mad_i64_i32 v[50:51], s[10:11], v22, s79, v[20:21]
	global_load_ushort v251, v[50:51], off offset:2048
	s_waitcnt lgkmcnt(0)
	s_barrier
	s_cmpk_eq_i32 s1, 0xffa0
	s_cbranch_scc1 .LBB0_731

; #define LAS __attribute__((address_space(3)))
; __device__ __forceinline__ bf16_t f2bf(float f) { unsigned u = __float_as_uint(f); u += 0x7FFFu + ((u >> 16) & 1u); return (bf16_t)(u >> 16); }
; __device__ __forceinline__ void lds_barrier() { asm volatile("s_waitcnt lgkmcnt(0)" ::: "memory"); __builtin_amdgcn_s_barrier(); asm volatile("" ::: "memory"); }
; template <bool HG>
; __device__ __forceinline__ void diag_item_A(const Params& p, int l, int seg, int h, LAS float* sm, int tid, int lane, int wave) {
;     ...
;         if (tid < K) {
;             float dd[TS], kk_[TS];
; #pragma unroll
;             for (int t = 0; t < TS; ++t) { dd[t] = bf[2048 + t * K + tid]; kk_[t] = bf[4096 + t * K + tid]; }
; #pragma unroll
;             for (int t = TS - 1; t >= 0; --t) { kT[tid * TP + t] = f2bf(kk_[t] * R); R *= dd[t]; }
;         }
;         { float vv_[EV];
; #pragma unroll
;           for (int e = 0; e < EV; ++e) vv_[e] = bf[6144 + tid + 512 * e];
; #pragma unroll
;           for (int e = 0; e < EV; ++e) { const int idx = tid + 512 * e; vT[(idx % V) * TP + (idx / V)] = f2bf(vv_[e]); } }
;         lds_barrier();
;         if (HG) {
;             const pg8::bf16x8 a = *(const LAS pg8::bf16x8*)(kT + (16 * wave + row) * TP + 8 * q);
; #pragma unroll
;             for (int n = 0; n < 4; ++n) acc[n] = __builtin_amdgcn_mfma_f32_16x16x32_bf16(a, *(const LAS pg8::bf16x8*)(vT + (16 * n + row) * TP + 8 * q), acc[n], 0, 0, 0);
;         } else if (wave < 6) {
;             const pg8::bf16x8 b = *(const LAS pg8::bf16x8*)(vT + (16 * wave + row) * TP + 8 * q);
; #pragma unroll
;             for (int m = 0; m < 3; ++m) acc[m] = __builtin_amdgcn_mfma_f32_16x16x32_bf16(*(const LAS pg8::bf16x8*)(kT + (16 * m + row) * TP + 8 * q), b, acc[m], 0, 0, 0);
;         }
;         if (sbi + 1 < SEG / TS) DG_STORE(cur ^ 1);
.LBB0_733:
	s_or_b64 exec, exec, s[10:11]
	ds_read2st64_b32 v[18:19], v24 offset0:216 offset1:224
	s_waitcnt lgkmcnt(0)
	v_bfe_u32 v20, v18, 16, 1
	v_add3_u32 v18, v18, v20, s61
	ds_write_b16_d16_hi v29, v18
	v_bfe_u32 v18, v19, 16, 1
	v_add3_u32 v18, v19, v18, s61
	ds_write_b16_d16_hi v28, v18
	s_waitcnt lgkmcnt(0)
	s_barrier
	ds_read_b128 v[38:41], v27
	ds_read_b128 v[18:21], v34
	s_waitcnt lgkmcnt(0)
	v_mfma_f32_16x16x32_bf16 v[18:21], v[38:41], v[18:21], v[6:9]
	s_nop 2
	ds_read_b128 v[6:9], v34 offset:1280
	s_waitcnt lgkmcnt(0)
	v_mfma_f32_16x16x32_bf16 v[10:13], v[38:41], v[6:9], v[10:13]
	ds_read_b128 v[6:9], v34 offset:2560
	s_waitcnt lgkmcnt(0)
	v_mfma_f32_16x16x32_bf16 v[6:9], v[38:41], v[6:9], v[14:17]
	s_nop 2
	ds_read_b128 v[14:17], v0
	s_waitcnt lgkmcnt(0)
	v_mfma_f32_16x16x32_bf16 v[2:5], v[38:41], v[14:17], v[2:5]
	s_waitcnt vmcnt(0)
	v_lshlrev_b32_e32 v14, 16, v246
	v_mul_f32_e32 v14, 0xbfb8aa3b, v14
	v_exp_f32_e32 v14, v14
	ds_read_b32 v15, v35
	v_add_f32_e32 v14, 1.0, v14
	v_rcp_f32_e32 v14, v14
	s_waitcnt lgkmcnt(0)
	v_sub_f32_e32 v16, 1.0, v15
	v_fmac_f32_e32 v15, v14, v16
	v_sub_f32_e32 v14, 1.0, v14
	v_mul_f32_e32 v14, v14, v16
	ds_write_b32 v24, v14 offset:16384
	v_lshlrev_b32_e32 v14, 16, v247
	v_mul_f32_e32 v14, 0xbfb8aa3b, v14
	v_exp_f32_e32 v14, v14
	v_max_f32_e32 v15, 0xda24260, v15
	ds_write_b32 v24, v15 offset:8192
	ds_read_b32 v15, v35
	v_add_f32_e32 v14, 1.0, v14
	v_rcp_f32_e32 v14, v14
	s_waitcnt lgkmcnt(0)
	v_sub_f32_e32 v16, 1.0, v15
	v_fmac_f32_e32 v15, v14, v16
	v_sub_f32_e32 v14, 1.0, v14
	v_mul_f32_e32 v14, v14, v16
	ds_write_b32 v24, v14 offset:18432
	v_lshlrev_b32_e32 v14, 16, v248
	v_mul_f32_e32 v14, 0xbfb8aa3b, v14
	v_exp_f32_e32 v14, v14
	v_max_f32_e32 v15, 0xda24260, v15
	ds_write_b32 v24, v15 offset:10240
	ds_read_b32 v15, v35
	v_add_f32_e32 v14, 1.0, v14
	v_rcp_f32_e32 v14, v14
	s_waitcnt lgkmcnt(0)
	v_sub_f32_e32 v16, 1.0, v15
	v_fmac_f32_e32 v15, v14, v16
	v_sub_f32_e32 v14, 1.0, v14
	v_mul_f32_e32 v14, v14, v16
	ds_write_b32 v24, v14 offset:20480
	v_lshlrev_b32_e32 v14, 16, v249
	v_mul_f32_e32 v14, 0xbfb8aa3b, v14
	v_exp_f32_e32 v14, v14
	v_max_f32_e32 v15, 0xda24260, v15
	ds_write_b32 v24, v15 offset:12288
	ds_read_b32 v15, v35
	v_add_f32_e32 v14, 1.0, v14
	v_rcp_f32_e32 v14, v14
	s_waitcnt lgkmcnt(0)
	v_sub_f32_e32 v16, 1.0, v15
	v_fmac_f32_e32 v15, v14, v16
	v_max_f32_e32 v15, 0xda24260, v15
	v_sub_f32_e32 v14, 1.0, v14
	ds_write_b32 v24, v15 offset:14336
	v_mul_f32_e32 v14, v14, v16
	v_lshlrev_b32_e32 v15, 16, v250
	ds_write2st64_b32 v24, v14, v15 offset0:88 offset1:96
	v_lshlrev_b32_e32 v14, 16, v251
	ds_write_b32 v24, v14 offset:26624
	s_waitcnt lgkmcnt(0)
	s_barrier
	s_and_saveexec_b64 s[10:11], s[8:9]
	s_cbranch_execz .LBB0_735
	ds_read2st64_b32 v[38:39], v24 offset0:32 offset1:34
	ds_read2st64_b32 v[40:41], v24 offset0:64 offset1:66
	ds_read2st64_b32 v[42:43], v24 offset0:36 offset1:38
	ds_read2st64_b32 v[44:45], v24 offset0:68 offset1:70
	ds_read2st64_b32 v[48:49], v24 offset0:40 offset1:42
	ds_read2st64_b32 v[50:51], v24 offset0:72 offset1:74
	ds_read2st64_b32 v[52:53], v24 offset0:44 offset1:46
	ds_read2st64_b32 v[54:55], v24 offset0:76 offset1:78
	ds_read2st64_b32 v[56:57], v24 offset0:48 offset1:50
	ds_read2st64_b32 v[14:15], v24 offset0:80 offset1:82
	ds_read2st64_b32 v[16:17], v24 offset0:52 offset1:54
	ds_read2st64_b32 v[58:59], v24 offset0:60 offset1:62
	ds_read2st64_b32 v[60:61], v24 offset0:84 offset1:86
	ds_read2st64_b32 v[62:63], v24 offset0:56 offset1:58
	ds_read2st64_b32 v[64:65], v24 offset0:88 offset1:90
	ds_read2st64_b32 v[66:67], v24 offset0:92 offset1:94
	s_waitcnt lgkmcnt(4)
	v_mul_f32_e32 v22, v23, v59
	v_mul_f32_e32 v59, v58, v22
	s_waitcnt lgkmcnt(2)
	v_mul_f32_e32 v58, v63, v59
	s_waitcnt lgkmcnt(1)
	v_pk_mul_f32 v[64:65], v[58:59], v[64:65]
	s_waitcnt lgkmcnt(0)
	v_pk_mul_f32 v[22:23], v[22:23], v[66:67]
	v_bfe_u32 v59, v64, 16, 1
	v_bfe_u32 v35, v23, 16, 1
	v_bfe_u32 v37, v22, 16, 1
	v_add3_u32 v35, v23, v35, s61
	v_mul_f32_e32 v23, v62, v58
	v_add3_u32 v37, v22, v37, s61
	v_mul_f32_e32 v22, v17, v23
	v_add3_u32 v63, v64, v59, s61
	v_mul_f32_e32 v59, v16, v22
	v_mul_f32_e32 v58, v57, v59
	v_pk_mul_f32 v[14:15], v[14:15], v[58:59]
	v_pk_mul_f32 v[16:17], v[60:61], v[22:23]
	v_bfe_u32 v47, v65, 16, 1
	v_bfe_u32 v22, v17, 16, 1
	v_bfe_u32 v23, v16, 16, 1
	v_bfe_u32 v57, v15, 16, 1
	v_bfe_u32 v59, v14, 16, 1
	v_add3_u32 v47, v65, v47, s61
	v_add3_u32 v14, v14, v59, s61
	v_add3_u32 v57, v15, v57, s61
	v_add3_u32 v15, v16, v23, s61
	v_add3_u32 v22, v17, v22, s61
	v_perm_b32 v17, v35, v37, s46
	v_perm_b32 v16, v47, v63, s46
	v_perm_b32 v15, v22, v15, s46
	v_perm_b32 v14, v57, v14, s46
	ds_write_b128 v36, v[14:17] offset:16
	v_mul_f32_e32 v15, v56, v58
	v_mul_f32_e32 v14, v53, v15
	v_mul_f32_e32 v17, v52, v14
	v_mul_f32_e32 v16, v49, v17
	v_pk_mul_f32 v[14:15], v[54:55], v[14:15]
	v_pk_mul_f32 v[22:23], v[50:51], v[16:17]
	v_bfe_u32 v17, v15, 16, 1
	v_bfe_u32 v35, v14, 16, 1
	v_add3_u32 v49, v15, v17, s61
	v_mul_f32_e32 v15, v48, v16
	v_bfe_u32 v37, v23, 16, 1
	v_add3_u32 v35, v14, v35, s61
	v_mul_f32_e32 v14, v43, v15
	v_bfe_u32 v47, v22, 16, 1
	v_add3_u32 v37, v23, v37, s61
	v_mul_f32_e32 v23, v42, v14
	v_add3_u32 v47, v22, v47, s61
	v_mul_f32_e32 v22, v39, v23
	v_pk_mul_f32 v[16:17], v[40:41], v[22:23]
	v_pk_mul_f32 v[14:15], v[44:45], v[14:15]
	v_bfe_u32 v40, v17, 16, 1
	v_bfe_u32 v23, v15, 16, 1
	v_bfe_u32 v39, v14, 16, 1
	v_bfe_u32 v41, v16, 16, 1
	v_add3_u32 v41, v16, v41, s61
	v_add3_u32 v40, v17, v40, s61
	v_add3_u32 v14, v14, v39, s61
	v_add3_u32 v15, v15, v23, s61
	v_perm_b32 v17, v49, v35, s46
	v_perm_b32 v16, v37, v47, s46
	v_perm_b32 v15, v15, v14, s46
	v_perm_b32 v14, v40, v41, s46
	v_mul_f32_e32 v23, v38, v22
	ds_write_b128 v36, v[14:17]

; __device__ __forceinline__ float bf2f(bf16_t b) { return __uint_as_float(((unsigned)b) << 16); }
; __device__ __forceinline__ bf16_t f2bf(float f) { unsigned u = __float_as_uint(f); u += 0x7FFFu + ((u >> 16) & 1u); return (bf16_t)(u >> 16); }
; __device__ __forceinline__ float sigm(float x) { return __builtin_amdgcn_rcpf(1.0f + __expf(-x)); }
; __device__ __forceinline__ void phase_rwprep(const Params& p, int l, LAS unsigned char* lds, int tid, int lane, int wave) {
;     ...
;             bf16_t cu_[9], pv_[9]; float mu_[9];
; #pragma unroll
;             for (int e = 0; e < 9; ++e) {
;                 const int idx = tid + 512 * e, t = idx / 288, j = idx % 288, tok = t0 + t;
;                 const int col = j < 256 ? 1152 + j : 1408 + (j - 256);
;                 const bf16_t* q = PR + (size_t)tok * PRW + col;
;                 cu_[e] = q[0];
;                 pv_[e] = tok > 0 ? q[-PRW] : (bf16_t)0;
;                 mu_[e] = j < 256 ? mu[col] : vmu[j - 256];
;             }
; #pragma unroll
;             for (int e = 0; e < 9; ++e) {
;                 const int idx = tid + 512 * e, t = idx / 288, j = idx % 288;
;                 const float cur = bf2f(cu_[e]), prev = bf2f(pv_[e]);
;                 const float z = cur + (prev - cur) * mu_[e];
;                 float val = j < 64 ? tanhf(z) : (j < 128 ? z : (j < 256 ? sigm(z) : (l > 0 ? z : 0.f)));
;                 Aimg[t * APITCH + j] = f2bf(val);
.LBB0_745:
	s_waitcnt lgkmcnt(14)
	v_add3_u32 v4, v134, s72, 1
	s_waitcnt lgkmcnt(0)
	s_barrier
	v_mad_i64_i32 v[2:3], s[10:11], v4, s79, v[66:67]
	global_load_ushort v27, v[2:3], off
	v_cmp_lt_i32_e32 vcc, 0, v4
	v_mov_b32_e32 v24, 0
	v_mov_b32_e32 v28, 0
	s_and_saveexec_b64 s[10:11], vcc
	s_cbranch_execz .LBB0_747
	global_load_ushort v28, v[2:3], off offset:-3072
.LBB0_747:
	s_or_b64 exec, exec, s[10:11]
	v_add3_u32 v4, v135, s72, 1
	v_mad_i64_i32 v[2:3], s[10:11], v4, s79, v[70:71]
	global_load_dword v29, v[68:69], off
	global_load_ushort v25, v[2:3], off
	v_cmp_lt_i32_e32 vcc, 0, v4
	s_and_saveexec_b64 s[10:11], vcc
	s_cbranch_execz .LBB0_749
	global_load_ushort v24, v[2:3], off offset:-3072
.LBB0_749:
	s_or_b64 exec, exec, s[10:11]
	v_add3_u32 v4, v136, s72, 1
	v_mad_i64_i32 v[2:3], s[10:11], v4, s79, v[74:75]
	global_load_dword v26, v[72:73], off
	global_load_ushort v21, v[2:3], off
	v_cmp_lt_i32_e32 vcc, 0, v4
	v_mov_b32_e32 v18, 0
	v_mov_b32_e32 v22, 0
	s_and_saveexec_b64 s[10:11], vcc
	s_cbranch_execz .LBB0_751
	global_load_ushort v22, v[2:3], off offset:-3072
.LBB0_751:
	s_or_b64 exec, exec, s[10:11]
	v_add3_u32 v4, v137, s72, 1
	v_mad_i64_i32 v[2:3], s[10:11], v4, s79, v[80:81]
	global_load_dword v23, v[76:77], off
	global_load_ushort v19, v[2:3], off
	v_cmp_lt_i32_e32 vcc, 0, v4
	s_and_saveexec_b64 s[10:11], vcc
	s_cbranch_execz .LBB0_753
	global_load_ushort v18, v[2:3], off offset:-3072
.LBB0_753:
	s_or_b64 exec, exec, s[10:11]
	v_add3_u32 v4, v138, s72, 1
	v_mad_i64_i32 v[2:3], s[10:11], v4, s79, v[84:85]
	global_load_dword v20, v[82:83], off
	global_load_ushort v15, v[2:3], off
	v_cmp_lt_i32_e32 vcc, 0, v4
	v_mov_b32_e32 v12, 0
	v_mov_b32_e32 v16, 0
	s_and_saveexec_b64 s[10:11], vcc
	s_cbranch_execz .LBB0_755
	global_load_ushort v16, v[2:3], off offset:-3072
.LBB0_755:
	s_or_b64 exec, exec, s[10:11]
	v_add3_u32 v4, v139, s72, 1
	v_mad_i64_i32 v[2:3], s[10:11], v4, s79, v[88:89]
	global_load_dword v17, v[86:87], off
	global_load_ushort v13, v[2:3], off
	v_cmp_lt_i32_e32 vcc, 0, v4
	s_and_saveexec_b64 s[10:11], vcc
	s_cbranch_execz .LBB0_757
	global_load_ushort v12, v[2:3], off offset:-3072
.LBB0_757:
	s_or_b64 exec, exec, s[10:11]
	v_add3_u32 v4, v140, s72, 1
	v_mad_i64_i32 v[2:3], s[10:11], v4, s79, v[92:93]
	global_load_dword v14, v[90:91], off
	global_load_ushort v9, v[2:3], off
	v_cmp_lt_i32_e32 vcc, 0, v4
	v_mov_b32_e32 v6, 0
	v_mov_b32_e32 v10, 0
	s_and_saveexec_b64 s[10:11], vcc
	s_cbranch_execz .LBB0_759
	global_load_ushort v10, v[2:3], off offset:-3072
.LBB0_759:
	s_or_b64 exec, exec, s[10:11]
	v_add3_u32 v4, v141, s72, 1
	v_mad_i64_i32 v[2:3], s[10:11], v4, s79, v[96:97]
	global_load_dword v11, v[94:95], off
	global_load_ushort v7, v[2:3], off
	v_cmp_lt_i32_e32 vcc, 0, v4
	s_and_saveexec_b64 s[10:11], vcc
	s_cbranch_execz .LBB0_761
	global_load_ushort v6, v[2:3], off offset:-3072
.LBB0_761:
	s_or_b64 exec, exec, s[10:11]
	v_add3_u32 v5, v142, s72, 1
	v_mad_i64_i32 v[2:3], s[10:11], v5, s79, v[100:101]
	global_load_dword v8, v[98:99], off
	global_load_ushort v4, v[2:3], off
	v_cmp_lt_i32_e32 vcc, 0, v5
	v_mov_b32_e32 v5, 0
	s_and_saveexec_b64 s[10:11], vcc
	s_cbranch_execz .LBB0_763
	global_load_ushort v5, v[2:3], off offset:-3072
.LBB0_763:
	s_or_b64 exec, exec, s[10:11]
	global_load_dword v2, v[102:103], off
	s_waitcnt vmcnt(0)
	v_lshlrev_b32_e32 v28, 16, v28
	v_lshlrev_b32_e32 v24, 16, v24
	v_lshlrev_b32_e32 v22, 16, v22
	v_lshlrev_b32_e32 v18, 16, v18
	v_lshlrev_b32_e32 v16, 16, v16
	v_lshlrev_b32_e32 v12, 16, v12
	v_lshlrev_b32_e32 v10, 16, v10
	v_lshlrev_b32_e32 v6, 16, v6
	v_lshlrev_b32_e32 v5, 16, v5
	v_lshlrev_b32_e32 v3, 16, v27
	v_sub_f32_e32 v27, v28, v3
	s_waitcnt vmcnt(16)
	v_fmac_f32_e32 v3, v29, v27
	s_and_saveexec_b64 s[10:11], s[8:9]
	s_xor_b64 s[10:11], exec, s[10:11]
	s_cbranch_execz .LBB0_771
	s_mov_b64 s[62:63], exec
	v_readlane_b32 s16, v254, 57
	v_readlane_b32 s17, v254, 58
	s_and_b64 s[16:17], s[62:63], s[16:17]
	s_mov_b64 exec, s[16:17]
	s_cbranch_execz .LBB0_770
	s_mov_b64 s[16:17], exec
	v_readlane_b32 s64, v255, 6
	v_readlane_b32 s65, v255, 7
	s_and_b64 s[64:65], s[16:17], s[64:65]
	s_xor_b64 s[16:17], s[64:65], s[16:17]
	s_mov_b64 exec, s[64:65]
	v_cndmask_b32_e64 v3, v3, 0, s[50:51]
	s_andn2_saveexec_b64 s[16:17], s[16:17]
	s_cbranch_execz .LBB0_769
	v_mul_f32_e32 v3, 0xbfb8aa3b, v3
	v_exp_f32_e32 v3, v3
	s_nop 0
	v_add_f32_e32 v3, 1.0, v3
	v_rcp_f32_e32 v3, v3

;     __device__ __forceinline__ const float* in(int i) const { return (const float*)(const __attribute__((address_space(1))) float*)ld(i); }
; __device__ __forceinline__ void phase_rwprep(const Params& p, int l, LAS unsigned char* lds, int tid, int lane, int wave) {
;     ...
;             const int c = tid, h = tid >> 6;
;             const float w0c = p.in(9)[l * RWW + c], a0c = p.in(11)[l * RWW + c];
;             const float v0c = l > 0 ? p.in(21)[lv * RWW + c] : 0.f;
;             const float mur = mu[c], muk = mu[384 + c], muv = mu[768 + c];
;             const float kkc = p.in(14)[l * RWW + c], kac = p.in(15)[l * RWW + c], rkc = p.in(16)[l * RWW + c];
;             bf16_t rr_[17], kr_[17], vr_[17], vf_[16];
; #pragma unroll
;             for (int t = 0; t < 17; ++t) {
;                 const int tok = t0 - 1 + t;
;                 if (tok >= 0) { const bf16_t* qq = PR + (size_t)tok * PRW + c; rr_[t] = qq[0]; kr_[t] = qq[384]; vr_[t] = qq[768]; }
;                 else { rr_[t] = 0; kr_[t] = 0; vr_[t] = 0; }
;             }
.LBB0_898:
	v_readlane_b32 s10, v254, 38
	global_load_dword v40, v[58:59], off
	global_load_dword v41, v[58:59], off offset:1536
	global_load_dword v44, v[58:59], off offset:3072
	v_mov_b32_e32 v2, s10
	ds_read_b128 v[2:5], v2
	s_cmp_lt_i32 s2, 1
	v_mov_b32_e32 v244, 0
	v_mov_b32_e32 v245, 0
	s_waitcnt lgkmcnt(0)
	v_readfirstlane_b32 s10, v2
	v_readfirstlane_b32 s11, v3
	s_nop 1
	v_lshl_add_u64 v[2:3], s[10:11], 0, v[128:129]
	v_readfirstlane_b32 s10, v4
	v_readfirstlane_b32 s11, v5
	global_load_dword v39, v[2:3], off
	s_nop 0
	v_lshl_add_u64 v[2:3], s[10:11], 0, v[128:129]
	v_readlane_b32 s10, v254, 39
	global_load_dword v37, v[2:3], off
	s_nop 0
	v_mov_b32_e32 v2, s10
	ds_read_b64 v[2:3], v2
	s_waitcnt lgkmcnt(0)
	v_readfirstlane_b32 s10, v2
	v_readfirstlane_b32 s11, v3
	s_nop 1
	v_lshl_add_u64 v[2:3], s[10:11], 0, v[128:129]
	global_load_dword v42, v[2:3], off
	s_cbranch_scc1 .LBB0_900
	v_mad_u64_u32 v[2:3], s[10:11], s72, v167, v[60:61]
	global_load_ushort v244, v[2:3], off
	global_load_ushort v245, v[2:3], off offset:768
	global_load_ushort v34, v[2:3], off offset:1536
.LBB0_900:
	s_add_i32 s10, s72, 1
	s_cmp_gt_i32 s2, -1
	v_mov_b32_e32 v240, 0
	s_cselect_b64 vcc, -1, 0
	s_cmp_lt_i32 s2, 0
	v_mov_b32_e32 v242, 0
	v_mov_b32_e32 v32, 0
	v_mov_b32_e32 v33, 0
	s_cbranch_scc1 .LBB0_902
	v_mad_u64_u32 v[2:3], s[16:17], s10, v167, v[60:61]
	global_load_ushort v242, v[2:3], off
	global_load_ushort v32, v[2:3], off offset:768
	global_load_ushort v33, v[2:3], off offset:1536
.LBB0_902:
	v_cndmask_b32_e64 v2, 0, 1, vcc
	v_cmp_ne_u32_e64 s[66:67], 1, v2
	s_andn2_b64 vcc, exec, vcc
	v_mov_b32_e32 v30, 0
	v_mov_b32_e32 v31, 0
	s_cbranch_vccnz .LBB0_904
	s_add_i32 s11, s72, 2
	v_mad_u64_u32 v[2:3], s[16:17], s11, v167, v[60:61]
	global_load_ushort v240, v[2:3], off
	global_load_ushort v30, v[2:3], off offset:768
	global_load_ushort v31, v[2:3], off offset:1536
.LBB0_904:
	v_mov_b32_e32 v236, 0
	s_and_b64 vcc, exec, s[66:67]
	v_mov_b32_e32 v238, 0
	v_mov_b32_e32 v28, 0
	v_mov_b32_e32 v29, 0
	s_cbranch_vccnz .LBB0_906
	s_add_i32 s11, s72, 3
	v_mad_u64_u32 v[2:3], s[16:17], s11, v167, v[60:61]
	global_load_ushort v238, v[2:3], off
	global_load_ushort v28, v[2:3], off offset:768
	global_load_ushort v29, v[2:3], off offset:1536
.LBB0_906:
	s_and_b64 vcc, exec, s[66:67]
	v_mov_b32_e32 v26, 0
	v_mov_b32_e32 v27, 0
	s_cbranch_vccnz .LBB0_908
	s_add_i32 s11, s72, 4
	v_mad_u64_u32 v[2:3], s[16:17], s11, v167, v[60:61]
	global_load_ushort v236, v[2:3], off
	global_load_ushort v26, v[2:3], off offset:768
	global_load_ushort v27, v[2:3], off offset:1536
.LBB0_908:
	v_mov_b32_e32 v232, 0
	s_and_b64 vcc, exec, s[66:67]
	v_mov_b32_e32 v234, 0
	v_mov_b32_e32 v24, 0
	v_mov_b32_e32 v25, 0
	s_cbranch_vccnz .LBB0_910
	s_add_i32 s11, s72, 5
	v_mad_u64_u32 v[2:3], s[16:17], s11, v167, v[60:61]
	global_load_ushort v234, v[2:3], off
	global_load_ushort v24, v[2:3], off offset:768
	global_load_ushort v25, v[2:3], off offset:1536
.LBB0_910:
	s_and_b64 vcc, exec, s[66:67]
	v_mov_b32_e32 v22, 0
	v_mov_b32_e32 v23, 0
	s_cbranch_vccnz .LBB0_912
	s_add_i32 s11, s72, 6
	v_mad_u64_u32 v[2:3], s[16:17], s11, v167, v[60:61]
	global_load_ushort v232, v[2:3], off
	global_load_ushort v22, v[2:3], off offset:768
	global_load_ushort v23, v[2:3], off offset:1536
.LBB0_912:
	v_mov_b32_e32 v228, 0
	s_and_b64 vcc, exec, s[66:67]
	v_mov_b32_e32 v230, 0
	v_mov_b32_e32 v20, 0
	v_mov_b32_e32 v21, 0
	s_cbranch_vccnz .LBB0_914
	s_add_i32 s11, s72, 7
	v_mad_u64_u32 v[2:3], s[16:17], s11, v167, v[60:61]
	global_load_ushort v230, v[2:3], off
	global_load_ushort v20, v[2:3], off offset:768
	global_load_ushort v21, v[2:3], off offset:1536
.LBB0_914:
	s_and_b64 vcc, exec, s[66:67]
	v_mov_b32_e32 v18, 0
	v_mov_b32_e32 v19, 0
	s_cbranch_vccnz .LBB0_916
	s_add_i32 s11, s72, 8
	v_mad_u64_u32 v[2:3], s[16:17], s11, v167, v[60:61]
	global_load_ushort v228, v[2:3], off
	global_load_ushort v18, v[2:3], off offset:768
	global_load_ushort v19, v[2:3], off offset:1536
.LBB0_916:
	v_mov_b32_e32 v55, 0
	s_and_b64 vcc, exec, s[66:67]
	v_mov_b32_e32 v226, 0
	v_mov_b32_e32 v16, 0
	v_mov_b32_e32 v17, 0
	s_cbranch_vccnz .LBB0_918
	s_add_i32 s11, s72, 9
	v_mad_u64_u32 v[2:3], s[16:17], s11, v167, v[60:61]
	global_load_ushort v226, v[2:3], off
	global_load_ushort v16, v[2:3], off offset:768
	global_load_ushort v17, v[2:3], off offset:1536
; __device__ __forceinline__ void phase_rwprep(const Params& p, int l, LAS unsigned char* lds, int tid, int lane, int wave) {
;     ...
;             bf16_t rr_[17], kr_[17], vr_[17], vf_[16];
; #pragma unroll
;             for (int t = 0; t < 17; ++t) {
;                 const int tok = t0 - 1 + t;
;                 if (tok >= 0) { const bf16_t* qq = PR + (size_t)tok * PRW + c; rr_[t] = qq[0]; kr_[t] = qq[384]; vr_[t] = qq[768]; }
;                 else { rr_[t] = 0; kr_[t] = 0; vr_[t] = 0; }
;             }
; #pragma unroll
;             for (int t = 0; t < 16; ++t) vf_[t] = (l > 0) ? VF[(size_t)(t0 + t) * RWW + c] : (bf16_t)0;
.LBB0_918:
	s_and_b64 vcc, exec, s[66:67]
	v_mov_b32_e32 v14, 0
	v_mov_b32_e32 v15, 0
	s_cbranch_vccnz .LBB0_920
	s_add_i32 s11, s72, 10
	v_mad_u64_u32 v[2:3], s[16:17], s11, v167, v[60:61]
	global_load_ushort v55, v[2:3], off
	global_load_ushort v14, v[2:3], off offset:768
	global_load_ushort v15, v[2:3], off offset:1536
.LBB0_920:
	v_mov_b32_e32 v51, 0
	s_and_b64 vcc, exec, s[66:67]
	v_mov_b32_e32 v53, 0
	v_mov_b32_e32 v12, 0
	v_mov_b32_e32 v13, 0
	s_cbranch_vccnz .LBB0_922
	s_add_i32 s11, s72, 11
	v_mad_u64_u32 v[2:3], s[16:17], s11, v167, v[60:61]
	global_load_ushort v53, v[2:3], off
	global_load_ushort v12, v[2:3], off offset:768
	global_load_ushort v13, v[2:3], off offset:1536
.LBB0_922:
	s_and_b64 vcc, exec, s[66:67]
	v_mov_b32_e32 v10, 0
	v_mov_b32_e32 v11, 0
	s_cbranch_vccnz .LBB0_924
	s_add_i32 s11, s72, 12
	v_mad_u64_u32 v[2:3], s[16:17], s11, v167, v[60:61]
	global_load_ushort v51, v[2:3], off
	global_load_ushort v10, v[2:3], off offset:768
	global_load_ushort v11, v[2:3], off offset:1536
.LBB0_924:
	v_mov_b32_e32 v47, 0
	s_and_b64 vcc, exec, s[66:67]
	v_mov_b32_e32 v49, 0
	v_mov_b32_e32 v8, 0
	v_mov_b32_e32 v9, 0
	s_cbranch_vccnz .LBB0_926
	s_add_i32 s11, s72, 13
	v_mad_u64_u32 v[2:3], s[16:17], s11, v167, v[60:61]
	global_load_ushort v49, v[2:3], off
	global_load_ushort v8, v[2:3], off offset:768
	global_load_ushort v9, v[2:3], off offset:1536
.LBB0_926:
	s_and_b64 vcc, exec, s[66:67]
	v_mov_b32_e32 v6, 0
	v_mov_b32_e32 v7, 0
	s_cbranch_vccnz .LBB0_928
	s_add_i32 s11, s72, 14
	v_mad_u64_u32 v[2:3], s[16:17], s11, v167, v[60:61]
	global_load_ushort v47, v[2:3], off
	global_load_ushort v6, v[2:3], off offset:768
	global_load_ushort v7, v[2:3], off offset:1536
.LBB0_928:
	v_mov_b32_e32 v45, 0
	s_and_b64 vcc, exec, s[66:67]
	v_mov_b32_e32 v46, 0
	v_mov_b32_e32 v4, 0
	v_mov_b32_e32 v5, 0
	s_cbranch_vccnz .LBB0_930
	s_add_i32 s11, s72, 15
	v_mad_u64_u32 v[2:3], s[16:17], s11, v167, v[60:61]
	global_load_ushort v46, v[2:3], off
	global_load_ushort v4, v[2:3], off offset:768
	global_load_ushort v5, v[2:3], off offset:1536
.LBB0_930:
	s_and_b64 vcc, exec, s[66:67]
	v_mov_b32_e32 v2, 0
	v_mov_b32_e32 v3, 0
	v_mov_b32_e32 v48, 0
	v_mov_b32_e32 v35, 0
	s_cbranch_vccnz .LBB0_932
	s_add_i32 s11, s72, 16
	v_mad_u64_u32 v[2:3], s[16:17], s11, v167, v[60:61]
	global_load_ushort v45, v[2:3], off
	global_load_ushort v48, v[2:3], off offset:768
	global_load_ushort v35, v[2:3], off offset:1536
.LBB0_932:
	s_waitcnt vmcnt(0)
	v_lshlrev_b32_e32 v244, 16, v244
	v_lshlrev_b32_e32 v245, 16, v245
	v_lshlrev_b32_e32 v34, 16, v34
	v_lshlrev_b32_e32 v242, 16, v242
	v_lshlrev_b32_e32 v32, 16, v32
	v_lshlrev_b32_e32 v33, 16, v33
	v_lshlrev_b32_e32 v240, 16, v240
	v_lshlrev_b32_e32 v30, 16, v30
	v_lshlrev_b32_e32 v31, 16, v31
	v_lshlrev_b32_e32 v238, 16, v238
	v_lshlrev_b32_e32 v28, 16, v28
	v_lshlrev_b32_e32 v29, 16, v29
	v_lshlrev_b32_e32 v236, 16, v236
	v_lshlrev_b32_e32 v26, 16, v26
	v_lshlrev_b32_e32 v27, 16, v27
	v_lshlrev_b32_e32 v234, 16, v234
	v_lshlrev_b32_e32 v24, 16, v24
	v_lshlrev_b32_e32 v25, 16, v25
	v_lshlrev_b32_e32 v232, 16, v232
	v_lshlrev_b32_e32 v22, 16, v22
	v_lshlrev_b32_e32 v23, 16, v23
	v_lshlrev_b32_e32 v230, 16, v230
	v_lshlrev_b32_e32 v20, 16, v20
	v_lshlrev_b32_e32 v21, 16, v21
	v_lshlrev_b32_e32 v228, 16, v228
	v_lshlrev_b32_e32 v18, 16, v18
	v_lshlrev_b32_e32 v19, 16, v19
	v_lshlrev_b32_e32 v226, 16, v226
	v_lshlrev_b32_e32 v16, 16, v16
	v_lshlrev_b32_e32 v17, 16, v17
	v_lshlrev_b32_e32 v55, 16, v55
	v_lshlrev_b32_e32 v14, 16, v14
	v_lshlrev_b32_e32 v15, 16, v15
	v_lshlrev_b32_e32 v53, 16, v53
	v_lshlrev_b32_e32 v12, 16, v12
	v_lshlrev_b32_e32 v13, 16, v13
	v_lshlrev_b32_e32 v51, 16, v51
	v_lshlrev_b32_e32 v10, 16, v10
	v_lshlrev_b32_e32 v11, 16, v11
	v_lshlrev_b32_e32 v49, 16, v49
	v_lshlrev_b32_e32 v8, 16, v8
	v_lshlrev_b32_e32 v9, 16, v9
	v_lshlrev_b32_e32 v47, 16, v47
	v_lshlrev_b32_e32 v6, 16, v6
	v_lshlrev_b32_e32 v7, 16, v7
	v_lshlrev_b32_e32 v46, 16, v46
	v_lshlrev_b32_e32 v4, 16, v4
	v_lshlrev_b32_e32 v5, 16, v5
	v_lshlrev_b32_e32 v45, 16, v45
	v_lshlrev_b32_e32 v2, 16, v48
	v_lshlrev_b32_e32 v3, 16, v35
	v_mov_b32_e32 v246, 0
	s_and_b64 vcc, exec, s[64:65]
	v_mov_b32_e32 v249, 0
	s_cbranch_vccz .LBB0_1045
	s_and_b64 vcc, exec, s[64:65]
	s_cbranch_vccz .LBB0_1046

; __device__ __forceinline__ float bf2f(bf16_t b) { return __uint_as_float(((unsigned)b) << 16); }
; __device__ __forceinline__ bf16_t f2bf(float f) { unsigned u = __float_as_uint(f); u += 0x7FFFu + ((u >> 16) & 1u); return (bf16_t)(u >> 16); }
; __device__ __forceinline__ float sigm(float x) { return __builtin_amdgcn_rcpf(1.0f + __expf(-x)); }
; __device__ __forceinline__ void phase_rwprep(const Params& p, int l, LAS unsigned char* lds, int tid, int lane, int wave) {
;     ...
;             for (int t = 0; t < 16; ++t) vf_[t] = (l > 0) ? VF[(size_t)(t0 + t) * RWW + c] : (bf16_t)0;
; #pragma unroll
;             for (int t = 0; t < 16; ++t) {
;                 const int tok = t0 + t;
;                 const float rc = bf2f(rr_[t + 1]), kc = bf2f(kr_[t + 1]), vc = bf2f(vr_[t + 1]);
;                 const float rp = bf2f(rr_[t]), kp = bf2f(kr_[t]), vp = bf2f(vr_[t]);
;                 const float r = rc + (rp - rc) * mur, k = kc + (kp - kc) * muk;
;                 float v = vc + (vp - vc) * muv;
;                 const size_t o = (size_t)tok * RWW + c;
;                 const float lw = w0c + outL[0 * 16 * RWW + t * RWW + c];
;                 const float a = sigm(a0c + outL[1 * 16 * RWW + t * RWW + c]);
;                 const float g = outL[2 * 16 * RWW + t * RWW + c];
;                 if (l == 0) VF[o] = f2bf(v);
;                 else { const float vf = bf2f(vf_[t]); v = v + (vf - v) * sigm(v0c + outL[3 * 16 * RWW + t * RWW + c]); }
.LBB0_948:
	s_add_i32 s11, s72, 16
	v_mad_i64_i32 v[250:251], s[16:17], s11, v172, v[62:63]
	global_load_ushort v48, v[250:251], off
.LBB0_949:
	s_waitcnt vmcnt(0)
	v_lshlrev_b32_e32 v48, 16, v48
	v_lshlrev_b32_e32 v249, 16, v249
	v_lshlrev_b32_e32 v246, 16, v246
	v_lshlrev_b32_e32 v243, 16, v243
	v_lshlrev_b32_e32 v241, 16, v241
	v_lshlrev_b32_e32 v239, 16, v239
	v_lshlrev_b32_e32 v237, 16, v237
	v_lshlrev_b32_e32 v235, 16, v235
	v_lshlrev_b32_e32 v233, 16, v233
	v_lshlrev_b32_e32 v231, 16, v231
	v_lshlrev_b32_e32 v229, 16, v229
	v_lshlrev_b32_e32 v227, 16, v227
	v_lshlrev_b32_e32 v225, 16, v225
	v_lshlrev_b32_e32 v54, 16, v54
	v_lshlrev_b32_e32 v52, 16, v52
	v_lshlrev_b32_e32 v50, 16, v50
	v_sub_f32_e32 v34, v34, v33
	s_waitcnt vmcnt(3)
	v_fma_f32 v250, v44, v34, v33
	ds_read2st64_b32 v[34:35], v191 offset0:64 offset1:160
	ds_read_b32 v247, v192
	s_mov_b64 s[16:17], -1
	s_and_b64 vcc, exec, s[56:57]
	s_cbranch_vccz .LBB0_951
	ds_read_b32 v248, v193
	v_sub_f32_e32 v249, v249, v250
	s_mov_b64 s[16:17], 0
	s_waitcnt lgkmcnt(0)
	v_add_f32_e32 v248, v43, v248
	v_mul_f32_e32 v248, 0xbfb8aa3b, v248
	v_exp_f32_e32 v248, v248
	s_nop 0
	v_add_f32_e32 v248, 1.0, v248
	v_rcp_f32_e32 v248, v248
	s_nop 0
	v_fma_f32 v248, v249, v248, v250
	v_bfe_u32 v249, v248, 16, 1
	v_add3_u32 v248, v248, v249, s61
	v_lshrrev_b32_e32 v248, 16, v248

; __device__ __forceinline__ void phase_rwprep(const Params& p, int l, LAS unsigned char* lds, int tid, int lane, int wave) {
;     ...
; #pragma unroll
;             for (int t = 0; t < 16; ++t) vf_[t] = (l > 0) ? VF[(size_t)(t0 + t) * RWW + c] : (bf16_t)0;
.LBB0_1045:
	v_mad_i64_i32 v[248:249], s[16:17], s10, v172, v[62:63]
	global_load_ushort v249, v[248:249], off
	s_and_b64 vcc, exec, s[64:65]
	s_cbranch_vccnz .LBB0_934
.LBB0_1046:
	s_add_i32 s11, s72, 2
	v_mad_i64_i32 v[246:247], s[16:17], s11, v172, v[62:63]
	global_load_ushort v246, v[246:247], off
	v_mov_b32_e32 v241, 0
	s_and_b64 vcc, exec, s[64:65]
	v_mov_b32_e32 v243, 0
	s_cbranch_vccnz .LBB0_935
.LBB0_1047:
	s_add_i32 s11, s72, 3
	v_mad_i64_i32 v[250:251], s[16:17], s11, v172, v[62:63]
	global_load_ushort v243, v[250:251], off
	s_and_b64 vcc, exec, s[64:65]
	s_cbranch_vccnz .LBB0_936
.LBB0_1048:
	s_add_i32 s11, s72, 4
	v_mad_i64_i32 v[250:251], s[16:17], s11, v172, v[62:63]
	global_load_ushort v241, v[250:251], off
	v_mov_b32_e32 v237, 0
	s_and_b64 vcc, exec, s[64:65]
	v_mov_b32_e32 v239, 0
	s_cbranch_vccnz .LBB0_937
.LBB0_1049:
	s_add_i32 s11, s72, 5
	v_mad_i64_i32 v[250:251], s[16:17], s11, v172, v[62:63]
	global_load_ushort v239, v[250:251], off
	s_and_b64 vcc, exec, s[64:65]
	s_cbranch_vccnz .LBB0_938
.LBB0_1050:
	s_add_i32 s11, s72, 6
	v_mad_i64_i32 v[250:251], s[16:17], s11, v172, v[62:63]
	global_load_ushort v237, v[250:251], off
	v_mov_b32_e32 v233, 0
	s_and_b64 vcc, exec, s[64:65]
	v_mov_b32_e32 v235, 0
	s_cbranch_vccnz .LBB0_939
.LBB0_1051:
	s_add_i32 s11, s72, 7
	v_mad_i64_i32 v[250:251], s[16:17], s11, v172, v[62:63]
	global_load_ushort v235, v[250:251], off
	s_and_b64 vcc, exec, s[64:65]
	s_cbranch_vccnz .LBB0_940
.LBB0_1052:
	s_add_i32 s11, s72, 8
	v_mad_i64_i32 v[250:251], s[16:17], s11, v172, v[62:63]
	global_load_ushort v233, v[250:251], off
	v_mov_b32_e32 v229, 0
	s_and_b64 vcc, exec, s[64:65]
	v_mov_b32_e32 v231, 0
	s_cbranch_vccnz .LBB0_941
.LBB0_1053:
	s_add_i32 s11, s72, 9
	v_mad_i64_i32 v[250:251], s[16:17], s11, v172, v[62:63]
	global_load_ushort v231, v[250:251], off
	s_and_b64 vcc, exec, s[64:65]
	s_cbranch_vccnz .LBB0_942
.LBB0_1054:
	s_add_i32 s11, s72, 10
	v_mad_i64_i32 v[250:251], s[16:17], s11, v172, v[62:63]
	global_load_ushort v229, v[250:251], off
	v_mov_b32_e32 v225, 0
	s_and_b64 vcc, exec, s[64:65]
	v_mov_b32_e32 v227, 0
	s_cbranch_vccnz .LBB0_943
.LBB0_1055:
	s_add_i32 s11, s72, 11
	v_mad_i64_i32 v[250:251], s[16:17], s11, v172, v[62:63]
	global_load_ushort v227, v[250:251], off
	s_and_b64 vcc, exec, s[64:65]
	s_cbranch_vccnz .LBB0_944
.LBB0_1056:
	s_add_i32 s11, s72, 12
	v_mad_i64_i32 v[250:251], s[16:17], s11, v172, v[62:63]
	global_load_ushort v225, v[250:251], off
	v_mov_b32_e32 v52, 0
	s_and_b64 vcc, exec, s[64:65]
	v_mov_b32_e32 v54, 0
	s_cbranch_vccnz .LBB0_945
.LBB0_1057:
	s_add_i32 s11, s72, 13
	v_mad_i64_i32 v[250:251], s[16:17], s11, v172, v[62:63]
	global_load_ushort v54, v[250:251], off
	s_and_b64 vcc, exec, s[64:65]
	s_cbranch_vccnz .LBB0_946
.LBB0_1058:
	s_add_i32 s11, s72, 14
	v_mad_i64_i32 v[250:251], s[16:17], s11, v172, v[62:63]
	global_load_ushort v52, v[250:251], off
	v_mov_b32_e32 v48, 0
	s_and_b64 vcc, exec, s[64:65]
	v_mov_b32_e32 v50, 0
	s_cbranch_vccnz .LBB0_947
.LBB0_1059:
	s_add_i32 s11, s72, 15
	v_mad_i64_i32 v[250:251], s[16:17], s11, v172, v[62:63]
	global_load_ushort v50, v[250:251], off
	s_and_b64 vcc, exec, s[64:65]
	s_cbranch_vccz .LBB0_948
	s_branch .LBB0_949
